# MFMA order within each 16-block changed to m,n,k (k0,k1 of one accumulator back-to-back) in all 9 GEMM K-loops
# speedup vs baseline: 1.1955x; 1.1955x over previous
.LBB0_1790:
	ds_read_b128 v[146:149], v159
	ds_read_b128 v[150:153], v159 offset:1024
	ds_read_b128 v[164:167], v159 offset:2048
	ds_read_b128 v[168:171], v159 offset:3072
	ds_read_b128 v[172:175], v160
	ds_read_b128 v[176:179], v160 offset:1024
	ds_read_b128 v[186:189], v160 offset:2048
	ds_read_b128 v[190:193], v160 offset:3072
	s_add_u32 s79, s6, 0xfff00080
	s_addc_u32 s80, s7, -1
	s_cmp_eq_u32 s78, 60
	s_cselect_b32 s91, s45, s80
	s_cselect_b32 s90, s74, s79
	s_cselect_b32 s89, s43, s77
	s_cselect_b32 s88, s75, s76
	v_lshl_add_u64 v[180:181], s[6:7], 0, v[138:139]
	s_add_i32 m0, s33, 0xc000
	ds_read_b128 v[194:197], v161
	ds_read_b128 v[198:201], v161 offset:1024
	ds_read_b128 v[202:205], v161 offset:2048
	ds_read_b128 v[206:209], v161 offset:3072
	ds_read_b128 v[210:213], v161 offset:4096
	ds_read_b128 v[214:217], v161 offset:5120
	ds_read_b128 v[218:221], v161 offset:6144
	ds_read_b128 v[222:225], v161 offset:7168
	global_load_lds_dwordx4 v[180:181], off
	v_lshl_add_u64 v[180:181], s[6:7], 0, v[140:141]
	s_add_i32 m0, s33, 0xe000
	s_nop 0
	global_load_lds_dwordx4 v[180:181], off
	s_waitcnt vmcnt(8)
	s_waitcnt lgkmcnt(0)
	s_barrier
	s_setprio 1
	s_waitcnt lgkmcnt(0)
	v_mfma_f32_16x16x32_bf16 v[126:129], v[146:149], v[194:197], v[126:129]
	v_mfma_f32_16x16x32_bf16 v[126:129], v[150:153], v[198:201], v[126:129]
	v_mfma_f32_16x16x32_bf16 v[122:125], v[164:167], v[194:197], v[122:125]
	v_mfma_f32_16x16x32_bf16 v[122:125], v[168:171], v[198:201], v[122:125]
	v_mfma_f32_16x16x32_bf16 v[114:117], v[146:149], v[202:205], v[114:117]
	v_mfma_f32_16x16x32_bf16 v[114:117], v[150:153], v[206:209], v[114:117]
	v_mfma_f32_16x16x32_bf16 v[106:109], v[164:167], v[202:205], v[106:109]
	v_mfma_f32_16x16x32_bf16 v[106:109], v[168:171], v[206:209], v[106:109]
	v_mfma_f32_16x16x32_bf16 v[98:101], v[146:149], v[210:213], v[98:101]
	v_mfma_f32_16x16x32_bf16 v[98:101], v[150:153], v[214:217], v[98:101]
	v_mfma_f32_16x16x32_bf16 v[90:93], v[164:167], v[210:213], v[90:93]
	v_mfma_f32_16x16x32_bf16 v[90:93], v[168:171], v[214:217], v[90:93]
	v_mfma_f32_16x16x32_bf16 v[82:85], v[146:149], v[218:221], v[82:85]
	v_mfma_f32_16x16x32_bf16 v[82:85], v[150:153], v[222:225], v[82:85]
	v_mfma_f32_16x16x32_bf16 v[74:77], v[164:167], v[218:221], v[74:77]
	v_mfma_f32_16x16x32_bf16 v[74:77], v[168:171], v[222:225], v[74:77]
	s_setprio 0
	s_setprio 1
	v_mfma_f32_16x16x32_bf16 v[118:121], v[172:175], v[194:197], v[118:121]
	v_mfma_f32_16x16x32_bf16 v[118:121], v[176:179], v[198:201], v[118:121]
	v_mfma_f32_16x16x32_bf16 v[110:113], v[186:189], v[194:197], v[110:113]
	v_mfma_f32_16x16x32_bf16 v[110:113], v[190:193], v[198:201], v[110:113]
	v_mfma_f32_16x16x32_bf16 v[102:105], v[172:175], v[202:205], v[102:105]
	v_mfma_f32_16x16x32_bf16 v[102:105], v[176:179], v[206:209], v[102:105]
	v_mfma_f32_16x16x32_bf16 v[94:97], v[186:189], v[202:205], v[94:97]
	v_mfma_f32_16x16x32_bf16 v[94:97], v[190:193], v[206:209], v[94:97]
	v_mfma_f32_16x16x32_bf16 v[86:89], v[172:175], v[210:213], v[86:89]
	v_mfma_f32_16x16x32_bf16 v[86:89], v[176:179], v[214:217], v[86:89]
	v_mfma_f32_16x16x32_bf16 v[78:81], v[186:189], v[210:213], v[78:81]
	v_mfma_f32_16x16x32_bf16 v[78:81], v[190:193], v[214:217], v[78:81]
	v_mfma_f32_16x16x32_bf16 v[70:73], v[172:175], v[218:221], v[70:73]
	v_mfma_f32_16x16x32_bf16 v[70:73], v[176:179], v[222:225], v[70:73]
	v_mfma_f32_16x16x32_bf16 v[66:69], v[186:189], v[218:221], v[66:69]
	v_mfma_f32_16x16x32_bf16 v[66:69], v[190:193], v[222:225], v[66:69]
	s_setprio 0
	s_barrier
	s_add_i32 s79, s69, s25
	v_lshl_add_u64 v[180:181], s[88:89], 0, v[132:133]
	s_mov_b32 m0, s79
	ds_read_b128 v[194:197], v161 offset:16384
	ds_read_b128 v[198:201], v161 offset:17408
	ds_read_b128 v[202:205], v161 offset:18432
	ds_read_b128 v[206:209], v161 offset:19456
	ds_read_b128 v[210:213], v161 offset:20480
	ds_read_b128 v[214:217], v161 offset:21504
	ds_read_b128 v[218:221], v161 offset:22528
	ds_read_b128 v[222:225], v161 offset:23552
	global_load_lds_dwordx4 v[180:181], off
	s_add_i32 m0, s79, 0x2000
	s_add_u32 s80, s88, 0x100000
	v_lshl_add_u64 v[226:227], s[88:89], 0, v[136:137]
	s_addc_u32 s81, s89, 0
	s_add_i32 s79, s70, s25
	global_load_lds_dwordx4 v[226:227], off
	v_lshl_add_u64 v[228:229], s[80:81], 0, v[132:133]
	s_mov_b32 m0, s79
	v_lshl_add_u64 v[230:231], s[90:91], 0, v[134:135]
	global_load_lds_dwordx4 v[228:229], off
	v_lshl_add_u64 v[228:229], s[80:81], 0, v[136:137]
	s_add_i32 m0, s79, 0x2000
	s_nop 0
	global_load_lds_dwordx4 v[228:229], off
	v_lshl_add_u64 v[228:229], s[90:91], 0, v[130:131]
	s_mov_b32 m0, s33
	s_nop 0
	global_load_lds_dwordx4 v[228:229], off
	s_mov_b32 m0, s35
	s_nop 0
	global_load_lds_dwordx4 v[230:231], off
	s_waitcnt vmcnt(8)
	s_waitcnt lgkmcnt(0)
	s_barrier
	s_setprio 1
	s_waitcnt lgkmcnt(0)
	v_mfma_f32_16x16x32_bf16 v[62:65], v[146:149], v[194:197], v[62:65]
	v_mfma_f32_16x16x32_bf16 v[62:65], v[150:153], v[198:201], v[62:65]
	v_mfma_f32_16x16x32_bf16 v[58:61], v[164:167], v[194:197], v[58:61]
	v_mfma_f32_16x16x32_bf16 v[58:61], v[168:171], v[198:201], v[58:61]
	v_mfma_f32_16x16x32_bf16 v[50:53], v[146:149], v[202:205], v[50:53]
	v_mfma_f32_16x16x32_bf16 v[50:53], v[150:153], v[206:209], v[50:53]
	v_mfma_f32_16x16x32_bf16 v[42:45], v[164:167], v[202:205], v[42:45]
	v_mfma_f32_16x16x32_bf16 v[42:45], v[168:171], v[206:209], v[42:45]
	v_mfma_f32_16x16x32_bf16 v[34:37], v[146:149], v[210:213], v[34:37]
	v_mfma_f32_16x16x32_bf16 v[34:37], v[150:153], v[214:217], v[34:37]
	v_mfma_f32_16x16x32_bf16 v[26:29], v[164:167], v[210:213], v[26:29]
	v_mfma_f32_16x16x32_bf16 v[26:29], v[168:171], v[214:217], v[26:29]
	v_mfma_f32_16x16x32_bf16 v[18:21], v[146:149], v[218:221], v[18:21]
	v_mfma_f32_16x16x32_bf16 v[18:21], v[150:153], v[222:225], v[18:21]
	v_mfma_f32_16x16x32_bf16 v[10:13], v[164:167], v[218:221], v[10:13]
	v_mfma_f32_16x16x32_bf16 v[10:13], v[168:171], v[222:225], v[10:13]
	s_setprio 0
	s_setprio 1
	v_mfma_f32_16x16x32_bf16 v[54:57], v[172:175], v[194:197], v[54:57]
	v_mfma_f32_16x16x32_bf16 v[54:57], v[176:179], v[198:201], v[54:57]
	v_mfma_f32_16x16x32_bf16 v[46:49], v[186:189], v[194:197], v[46:49]
	v_mfma_f32_16x16x32_bf16 v[46:49], v[190:193], v[198:201], v[46:49]
	v_mfma_f32_16x16x32_bf16 v[38:41], v[172:175], v[202:205], v[38:41]
	v_mfma_f32_16x16x32_bf16 v[38:41], v[176:179], v[206:209], v[38:41]
	v_mfma_f32_16x16x32_bf16 v[30:33], v[186:189], v[202:205], v[30:33]
	v_mfma_f32_16x16x32_bf16 v[30:33], v[190:193], v[206:209], v[30:33]
	v_mfma_f32_16x16x32_bf16 v[22:25], v[172:175], v[210:213], v[22:25]
	v_mfma_f32_16x16x32_bf16 v[22:25], v[176:179], v[214:217], v[22:25]
	v_mfma_f32_16x16x32_bf16 v[14:17], v[186:189], v[210:213], v[14:17]
	v_mfma_f32_16x16x32_bf16 v[14:17], v[190:193], v[214:217], v[14:17]
	v_mfma_f32_16x16x32_bf16 v[6:9], v[172:175], v[218:221], v[6:9]
	v_mfma_f32_16x16x32_bf16 v[6:9], v[176:179], v[222:225], v[6:9]
	v_mfma_f32_16x16x32_bf16 v[2:5], v[186:189], v[218:221], v[2:5]
	v_mfma_f32_16x16x32_bf16 v[2:5], v[190:193], v[222:225], v[2:5]
	s_setprio 0
	s_barrier
	s_add_i32 s79, 0, 0x18000
	s_add_i32 s82, 0, 0x1c000
	v_add_u32_e32 v168, s79, v155
	v_add_u32_e32 v183, s82, v155
	ds_read_b128 v[146:149], v168
	ds_read_b128 v[150:153], v168 offset:1024
	ds_read_b128 v[164:167], v168 offset:2048
	ds_read_b128 v[168:171], v168 offset:3072
	ds_read_b128 v[172:175], v183
	ds_read_b128 v[176:179], v183 offset:1024
	ds_read_b128 v[186:189], v183 offset:2048
	ds_read_b128 v[190:193], v183 offset:3072
	s_add_u32 s80, s90, 0x100000
	s_addc_u32 s81, s91, 0
	s_mov_b32 m0, s59
	v_lshl_add_u64 v[232:233], s[80:81], 0, v[130:131]
	ds_read_b128 v[194:197], v161 offset:32768
	ds_read_b128 v[198:201], v161 offset:33792
	ds_read_b128 v[202:205], v161 offset:34816
	ds_read_b128 v[206:209], v161 offset:35840
	ds_read_b128 v[210:213], v161 offset:36864
	ds_read_b128 v[214:217], v161 offset:37888
	ds_read_b128 v[218:221], v161 offset:38912
	ds_read_b128 v[222:225], v161 offset:39936
	global_load_lds_dwordx4 v[232:233], off
	v_lshl_add_u64 v[232:233], s[80:81], 0, v[134:135]
	s_mov_b32 m0, s62
	s_nop 0
	global_load_lds_dwordx4 v[232:233], off
	s_waitcnt vmcnt(8)
	s_waitcnt lgkmcnt(0)
	s_barrier
	s_setprio 1
	s_waitcnt lgkmcnt(0)
	v_mfma_f32_16x16x32_bf16 v[126:129], v[146:149], v[194:197], v[126:129]
	v_mfma_f32_16x16x32_bf16 v[126:129], v[150:153], v[198:201], v[126:129]
	v_mfma_f32_16x16x32_bf16 v[122:125], v[164:167], v[194:197], v[122:125]
	v_mfma_f32_16x16x32_bf16 v[122:125], v[168:171], v[198:201], v[122:125]
	v_mfma_f32_16x16x32_bf16 v[114:117], v[146:149], v[202:205], v[114:117]
	v_mfma_f32_16x16x32_bf16 v[114:117], v[150:153], v[206:209], v[114:117]
	v_mfma_f32_16x16x32_bf16 v[106:109], v[164:167], v[202:205], v[106:109]
	v_mfma_f32_16x16x32_bf16 v[106:109], v[168:171], v[206:209], v[106:109]
	v_mfma_f32_16x16x32_bf16 v[98:101], v[146:149], v[210:213], v[98:101]
	v_mfma_f32_16x16x32_bf16 v[98:101], v[150:153], v[214:217], v[98:101]
	v_mfma_f32_16x16x32_bf16 v[90:93], v[164:167], v[210:213], v[90:93]
	v_mfma_f32_16x16x32_bf16 v[90:93], v[168:171], v[214:217], v[90:93]
	v_mfma_f32_16x16x32_bf16 v[82:85], v[146:149], v[218:221], v[82:85]
	v_mfma_f32_16x16x32_bf16 v[82:85], v[150:153], v[222:225], v[82:85]
	v_mfma_f32_16x16x32_bf16 v[74:77], v[164:167], v[218:221], v[74:77]
	v_mfma_f32_16x16x32_bf16 v[74:77], v[168:171], v[222:225], v[74:77]
	s_setprio 0
	s_setprio 1
	v_mfma_f32_16x16x32_bf16 v[118:121], v[172:175], v[194:197], v[118:121]
	v_mfma_f32_16x16x32_bf16 v[118:121], v[176:179], v[198:201], v[118:121]
	v_mfma_f32_16x16x32_bf16 v[110:113], v[186:189], v[194:197], v[110:113]
	v_mfma_f32_16x16x32_bf16 v[110:113], v[190:193], v[198:201], v[110:113]
	v_mfma_f32_16x16x32_bf16 v[102:105], v[172:175], v[202:205], v[102:105]
	v_mfma_f32_16x16x32_bf16 v[102:105], v[176:179], v[206:209], v[102:105]
	v_mfma_f32_16x16x32_bf16 v[94:97], v[186:189], v[202:205], v[94:97]
	v_mfma_f32_16x16x32_bf16 v[94:97], v[190:193], v[206:209], v[94:97]
	v_mfma_f32_16x16x32_bf16 v[86:89], v[172:175], v[210:213], v[86:89]
	v_mfma_f32_16x16x32_bf16 v[86:89], v[176:179], v[214:217], v[86:89]
	v_mfma_f32_16x16x32_bf16 v[78:81], v[186:189], v[210:213], v[78:81]
	v_mfma_f32_16x16x32_bf16 v[78:81], v[190:193], v[214:217], v[78:81]
	v_mfma_f32_16x16x32_bf16 v[70:73], v[172:175], v[218:221], v[70:73]
	v_mfma_f32_16x16x32_bf16 v[70:73], v[176:179], v[222:225], v[70:73]
	v_mfma_f32_16x16x32_bf16 v[66:69], v[186:189], v[218:221], v[66:69]
	v_mfma_f32_16x16x32_bf16 v[66:69], v[190:193], v[222:225], v[66:69]
	s_setprio 0
	s_barrier
	s_add_i32 s79, s79, s25
	v_lshl_add_u64 v[180:181], v[180:181], 0, s[28:29]
	s_mov_b32 m0, s79
	ds_read_b128 v[194:197], v161 offset:49152
	ds_read_b128 v[198:201], v161 offset:50176
	ds_read_b128 v[202:205], v161 offset:51200
	ds_read_b128 v[206:209], v161 offset:52224
	ds_read_b128 v[210:213], v161 offset:53248
	ds_read_b128 v[214:217], v161 offset:54272
	ds_read_b128 v[218:221], v161 offset:55296
	ds_read_b128 v[222:225], v161 offset:56320
	global_load_lds_dwordx4 v[180:181], off
	s_add_i32 m0, s79, 0x2000
	s_add_u32 s80, s88, 0x100080
	v_lshl_add_u64 v[180:181], v[226:227], 0, s[28:29]
	s_addc_u32 s81, s89, 0
	s_add_i32 s79, s82, s25
	global_load_lds_dwordx4 v[180:181], off
	v_lshl_add_u64 v[180:181], s[80:81], 0, v[132:133]
	s_mov_b32 m0, s79
	s_nop 0
	global_load_lds_dwordx4 v[180:181], off
	v_lshl_add_u64 v[180:181], s[80:81], 0, v[136:137]
	s_add_i32 m0, s79, 0x2000
	s_nop 0
	global_load_lds_dwordx4 v[180:181], off
	v_lshl_add_u64 v[180:181], v[228:229], 0, s[28:29]
	s_mov_b32 m0, s66
	s_nop 0
	global_load_lds_dwordx4 v[180:181], off
	v_lshl_add_u64 v[180:181], v[230:231], 0, s[28:29]
	s_mov_b32 m0, s67
	s_nop 0
	global_load_lds_dwordx4 v[180:181], off
	s_waitcnt vmcnt(8)
	s_waitcnt lgkmcnt(0)
	s_barrier
	s_setprio 1
	s_waitcnt lgkmcnt(0)
	v_mfma_f32_16x16x32_bf16 v[62:65], v[146:149], v[194:197], v[62:65]
	v_mfma_f32_16x16x32_bf16 v[62:65], v[150:153], v[198:201], v[62:65]
	v_mfma_f32_16x16x32_bf16 v[58:61], v[164:167], v[194:197], v[58:61]
	v_mfma_f32_16x16x32_bf16 v[58:61], v[168:171], v[198:201], v[58:61]
	v_mfma_f32_16x16x32_bf16 v[50:53], v[146:149], v[202:205], v[50:53]
	v_mfma_f32_16x16x32_bf16 v[50:53], v[150:153], v[206:209], v[50:53]
	v_mfma_f32_16x16x32_bf16 v[42:45], v[164:167], v[202:205], v[42:45]
	v_mfma_f32_16x16x32_bf16 v[42:45], v[168:171], v[206:209], v[42:45]
	v_mfma_f32_16x16x32_bf16 v[34:37], v[146:149], v[210:213], v[34:37]
	v_mfma_f32_16x16x32_bf16 v[34:37], v[150:153], v[214:217], v[34:37]
	v_mfma_f32_16x16x32_bf16 v[26:29], v[164:167], v[210:213], v[26:29]
	v_mfma_f32_16x16x32_bf16 v[26:29], v[168:171], v[214:217], v[26:29]
	v_mfma_f32_16x16x32_bf16 v[18:21], v[146:149], v[218:221], v[18:21]
	v_mfma_f32_16x16x32_bf16 v[18:21], v[150:153], v[222:225], v[18:21]
	v_mfma_f32_16x16x32_bf16 v[10:13], v[164:167], v[218:221], v[10:13]
	v_mfma_f32_16x16x32_bf16 v[10:13], v[168:171], v[222:225], v[10:13]
	s_setprio 0
	s_setprio 1
	v_mfma_f32_16x16x32_bf16 v[54:57], v[172:175], v[194:197], v[54:57]
	v_mfma_f32_16x16x32_bf16 v[54:57], v[176:179], v[198:201], v[54:57]
	v_mfma_f32_16x16x32_bf16 v[46:49], v[186:189], v[194:197], v[46:49]
	v_mfma_f32_16x16x32_bf16 v[46:49], v[190:193], v[198:201], v[46:49]
	v_mfma_f32_16x16x32_bf16 v[38:41], v[172:175], v[202:205], v[38:41]
	v_mfma_f32_16x16x32_bf16 v[38:41], v[176:179], v[206:209], v[38:41]
	v_mfma_f32_16x16x32_bf16 v[30:33], v[186:189], v[202:205], v[30:33]
	v_mfma_f32_16x16x32_bf16 v[30:33], v[190:193], v[206:209], v[30:33]
	v_mfma_f32_16x16x32_bf16 v[22:25], v[172:175], v[210:213], v[22:25]
	v_mfma_f32_16x16x32_bf16 v[22:25], v[176:179], v[214:217], v[22:25]
	v_mfma_f32_16x16x32_bf16 v[14:17], v[186:189], v[210:213], v[14:17]
	v_mfma_f32_16x16x32_bf16 v[14:17], v[190:193], v[214:217], v[14:17]
	v_mfma_f32_16x16x32_bf16 v[6:9], v[172:175], v[218:221], v[6:9]
	v_mfma_f32_16x16x32_bf16 v[6:9], v[176:179], v[222:225], v[6:9]
	v_mfma_f32_16x16x32_bf16 v[2:5], v[186:189], v[218:221], v[2:5]
	v_mfma_f32_16x16x32_bf16 v[2:5], v[190:193], v[222:225], v[2:5]
	s_setprio 0
	s_barrier
	s_add_i32 s78, s78, 2
	s_add_u32 s6, s6, 0x100
	s_addc_u32 s7, s7, 0
	s_add_u32 s76, s76, 0x100
	s_addc_u32 s77, s77, 0
	s_cmp_gt_u32 s78, 61
	s_cbranch_scc0 .LBB0_1790
	s_and_b64 vcc, exec, s[40:41]
	s_cbranch_vccz .LBB0_1793
	s_barrier

.LBB0_2109:
	ds_read_b128 v[130:133], v155
	ds_read_b128 v[134:137], v155 offset:1024
	ds_read_b128 v[138:141], v155 offset:2048
	ds_read_b128 v[142:145], v155 offset:3072
	ds_read_b128 v[166:169], v176
	ds_read_b128 v[170:173], v176 offset:1024
	ds_read_b128 v[186:189], v176 offset:2048
	ds_read_b128 v[190:193], v176 offset:3072
	s_add_u32 s74, s50, 0xfff00080
	s_addc_u32 s75, s51, -1
	s_cmp_eq_u32 s73, 60
	s_cselect_b32 s85, s26, s75
	s_cselect_b32 s84, s45, s74
	s_cselect_b32 s83, s43, s72
	s_cselect_b32 s82, s70, s71
	v_lshl_add_u64 v[180:181], s[50:51], 0, v[158:159]
	s_add_i32 m0, s23, 0xc000
	ds_read_b128 v[194:197], v177
	ds_read_b128 v[198:201], v177 offset:1024
	ds_read_b128 v[202:205], v177 offset:2048
	ds_read_b128 v[206:209], v177 offset:3072
	ds_read_b128 v[210:213], v177 offset:4096
	ds_read_b128 v[214:217], v177 offset:5120
	ds_read_b128 v[218:221], v177 offset:6144
	ds_read_b128 v[222:225], v177 offset:7168
	global_load_lds_dwordx4 v[180:181], off
	v_lshl_add_u64 v[180:181], s[50:51], 0, v[160:161]
	s_add_i32 m0, s23, 0xe000
	s_nop 0
	global_load_lds_dwordx4 v[180:181], off
	s_waitcnt vmcnt(8)
	s_waitcnt lgkmcnt(0)
	s_barrier
	s_setprio 1
	s_waitcnt lgkmcnt(0)
	v_mfma_f32_16x16x32_bf16 v[126:129], v[130:133], v[194:197], v[126:129]
	v_mfma_f32_16x16x32_bf16 v[126:129], v[134:137], v[198:201], v[126:129]
	v_mfma_f32_16x16x32_bf16 v[122:125], v[138:141], v[194:197], v[122:125]
	v_mfma_f32_16x16x32_bf16 v[122:125], v[142:145], v[198:201], v[122:125]
	v_mfma_f32_16x16x32_bf16 v[110:113], v[130:133], v[202:205], v[110:113]
	v_mfma_f32_16x16x32_bf16 v[110:113], v[134:137], v[206:209], v[110:113]
	v_mfma_f32_16x16x32_bf16 v[106:109], v[138:141], v[202:205], v[106:109]
	v_mfma_f32_16x16x32_bf16 v[106:109], v[142:145], v[206:209], v[106:109]
	v_mfma_f32_16x16x32_bf16 v[94:97], v[130:133], v[210:213], v[94:97]
	v_mfma_f32_16x16x32_bf16 v[94:97], v[134:137], v[214:217], v[94:97]
	v_mfma_f32_16x16x32_bf16 v[90:93], v[138:141], v[210:213], v[90:93]
	v_mfma_f32_16x16x32_bf16 v[90:93], v[142:145], v[214:217], v[90:93]
	v_mfma_f32_16x16x32_bf16 v[78:81], v[130:133], v[218:221], v[78:81]
	v_mfma_f32_16x16x32_bf16 v[78:81], v[134:137], v[222:225], v[78:81]
	v_mfma_f32_16x16x32_bf16 v[74:77], v[138:141], v[218:221], v[74:77]
	v_mfma_f32_16x16x32_bf16 v[74:77], v[142:145], v[222:225], v[74:77]
	s_setprio 0
	s_setprio 1
	v_mfma_f32_16x16x32_bf16 v[118:121], v[166:169], v[194:197], v[118:121]
	v_mfma_f32_16x16x32_bf16 v[118:121], v[170:173], v[198:201], v[118:121]
	v_mfma_f32_16x16x32_bf16 v[114:117], v[186:189], v[194:197], v[114:117]
	v_mfma_f32_16x16x32_bf16 v[114:117], v[190:193], v[198:201], v[114:117]
	v_mfma_f32_16x16x32_bf16 v[102:105], v[166:169], v[202:205], v[102:105]
	v_mfma_f32_16x16x32_bf16 v[102:105], v[170:173], v[206:209], v[102:105]
	v_mfma_f32_16x16x32_bf16 v[98:101], v[186:189], v[202:205], v[98:101]
	v_mfma_f32_16x16x32_bf16 v[98:101], v[190:193], v[206:209], v[98:101]
	v_mfma_f32_16x16x32_bf16 v[86:89], v[166:169], v[210:213], v[86:89]
	v_mfma_f32_16x16x32_bf16 v[86:89], v[170:173], v[214:217], v[86:89]
	v_mfma_f32_16x16x32_bf16 v[82:85], v[186:189], v[210:213], v[82:85]
	v_mfma_f32_16x16x32_bf16 v[82:85], v[190:193], v[214:217], v[82:85]
	v_mfma_f32_16x16x32_bf16 v[70:73], v[166:169], v[218:221], v[70:73]
	v_mfma_f32_16x16x32_bf16 v[70:73], v[170:173], v[222:225], v[70:73]
	v_mfma_f32_16x16x32_bf16 v[66:69], v[186:189], v[218:221], v[66:69]
	v_mfma_f32_16x16x32_bf16 v[66:69], v[190:193], v[222:225], v[66:69]
	s_setprio 0
	s_barrier
	s_add_i32 s74, s67, s3
	v_lshl_add_u64 v[180:181], s[82:83], 0, v[148:149]
	s_mov_b32 m0, s74
	ds_read_b128 v[194:197], v177 offset:16384
	ds_read_b128 v[198:201], v177 offset:17408
	ds_read_b128 v[202:205], v177 offset:18432
	ds_read_b128 v[206:209], v177 offset:19456
	ds_read_b128 v[210:213], v177 offset:20480
	ds_read_b128 v[214:217], v177 offset:21504
	ds_read_b128 v[218:221], v177 offset:22528
	ds_read_b128 v[222:225], v177 offset:23552
	global_load_lds_dwordx4 v[180:181], off
	s_add_i32 m0, s74, 0x2000
	s_add_u32 s74, s82, 0x100000
	v_lshl_add_u64 v[226:227], s[82:83], 0, v[152:153]
	s_addc_u32 s75, s83, 0
	s_add_i32 s76, s68, s3
	global_load_lds_dwordx4 v[226:227], off
	v_lshl_add_u64 v[228:229], s[74:75], 0, v[148:149]
	s_mov_b32 m0, s76
	v_lshl_add_u64 v[230:231], s[84:85], 0, v[150:151]
	global_load_lds_dwordx4 v[228:229], off
	v_lshl_add_u64 v[228:229], s[74:75], 0, v[152:153]
	s_add_i32 m0, s76, 0x2000
	s_nop 0
	global_load_lds_dwordx4 v[228:229], off
	v_lshl_add_u64 v[228:229], s[84:85], 0, v[146:147]
	s_mov_b32 m0, s23
	s_nop 0
	global_load_lds_dwordx4 v[228:229], off
	s_mov_b32 m0, s25
	s_nop 0
	global_load_lds_dwordx4 v[230:231], off
	s_waitcnt vmcnt(8)
	s_waitcnt lgkmcnt(0)
	s_barrier
	s_setprio 1
	s_waitcnt lgkmcnt(0)
	v_mfma_f32_16x16x32_bf16 v[62:65], v[130:133], v[194:197], v[62:65]
	v_mfma_f32_16x16x32_bf16 v[62:65], v[134:137], v[198:201], v[62:65]
	v_mfma_f32_16x16x32_bf16 v[58:61], v[138:141], v[194:197], v[58:61]
	v_mfma_f32_16x16x32_bf16 v[58:61], v[142:145], v[198:201], v[58:61]
	v_mfma_f32_16x16x32_bf16 v[46:49], v[130:133], v[202:205], v[46:49]
	v_mfma_f32_16x16x32_bf16 v[46:49], v[134:137], v[206:209], v[46:49]
	v_mfma_f32_16x16x32_bf16 v[42:45], v[138:141], v[202:205], v[42:45]
	v_mfma_f32_16x16x32_bf16 v[42:45], v[142:145], v[206:209], v[42:45]
	v_mfma_f32_16x16x32_bf16 v[30:33], v[130:133], v[210:213], v[30:33]
	v_mfma_f32_16x16x32_bf16 v[30:33], v[134:137], v[214:217], v[30:33]
	v_mfma_f32_16x16x32_bf16 v[26:29], v[138:141], v[210:213], v[26:29]
	v_mfma_f32_16x16x32_bf16 v[26:29], v[142:145], v[214:217], v[26:29]
	v_mfma_f32_16x16x32_bf16 v[14:17], v[130:133], v[218:221], v[14:17]
	v_mfma_f32_16x16x32_bf16 v[14:17], v[134:137], v[222:225], v[14:17]
	v_mfma_f32_16x16x32_bf16 v[10:13], v[138:141], v[218:221], v[10:13]
	v_mfma_f32_16x16x32_bf16 v[10:13], v[142:145], v[222:225], v[10:13]
	s_setprio 0
	s_setprio 1
	v_mfma_f32_16x16x32_bf16 v[54:57], v[166:169], v[194:197], v[54:57]
	v_mfma_f32_16x16x32_bf16 v[54:57], v[170:173], v[198:201], v[54:57]
	v_mfma_f32_16x16x32_bf16 v[50:53], v[186:189], v[194:197], v[50:53]
	v_mfma_f32_16x16x32_bf16 v[50:53], v[190:193], v[198:201], v[50:53]
	v_mfma_f32_16x16x32_bf16 v[38:41], v[166:169], v[202:205], v[38:41]
	v_mfma_f32_16x16x32_bf16 v[38:41], v[170:173], v[206:209], v[38:41]
	v_mfma_f32_16x16x32_bf16 v[34:37], v[186:189], v[202:205], v[34:37]
	v_mfma_f32_16x16x32_bf16 v[34:37], v[190:193], v[206:209], v[34:37]
	v_mfma_f32_16x16x32_bf16 v[22:25], v[166:169], v[210:213], v[22:25]
	v_mfma_f32_16x16x32_bf16 v[22:25], v[170:173], v[214:217], v[22:25]
	v_mfma_f32_16x16x32_bf16 v[18:21], v[186:189], v[210:213], v[18:21]
	v_mfma_f32_16x16x32_bf16 v[18:21], v[190:193], v[214:217], v[18:21]
	v_mfma_f32_16x16x32_bf16 v[6:9], v[166:169], v[218:221], v[6:9]
	v_mfma_f32_16x16x32_bf16 v[6:9], v[170:173], v[222:225], v[6:9]
	v_mfma_f32_16x16x32_bf16 v[2:5], v[186:189], v[218:221], v[2:5]
	v_mfma_f32_16x16x32_bf16 v[2:5], v[190:193], v[222:225], v[2:5]
	s_setprio 0
	s_barrier
	s_add_i32 s76, 0, 0x18000
	s_add_i32 s77, 0, 0x1c000
	v_add_u32_e32 v142, s76, v174
	v_add_u32_e32 v179, s77, v174
	ds_read_b128 v[130:133], v142
	ds_read_b128 v[134:137], v142 offset:1024
	ds_read_b128 v[138:141], v142 offset:2048
	ds_read_b128 v[142:145], v142 offset:3072
	ds_read_b128 v[166:169], v179
	ds_read_b128 v[170:173], v179 offset:1024
	ds_read_b128 v[186:189], v179 offset:2048
	ds_read_b128 v[190:193], v179 offset:3072
	s_add_u32 s74, s84, 0x100000
	s_addc_u32 s75, s85, 0
	s_mov_b32 m0, s33
	v_lshl_add_u64 v[232:233], s[74:75], 0, v[146:147]
	ds_read_b128 v[194:197], v177 offset:32768
	ds_read_b128 v[198:201], v177 offset:33792
	ds_read_b128 v[202:205], v177 offset:34816
	ds_read_b128 v[206:209], v177 offset:35840
	ds_read_b128 v[210:213], v177 offset:36864
	ds_read_b128 v[214:217], v177 offset:37888
	ds_read_b128 v[218:221], v177 offset:38912
	ds_read_b128 v[222:225], v177 offset:39936
	global_load_lds_dwordx4 v[232:233], off
	v_lshl_add_u64 v[232:233], s[74:75], 0, v[150:151]
	s_mov_b32 m0, s35
	s_nop 0
	global_load_lds_dwordx4 v[232:233], off
	s_waitcnt vmcnt(8)
	s_waitcnt lgkmcnt(0)
	s_barrier
	s_setprio 1
	s_waitcnt lgkmcnt(0)
	v_mfma_f32_16x16x32_bf16 v[126:129], v[130:133], v[194:197], v[126:129]
	v_mfma_f32_16x16x32_bf16 v[126:129], v[134:137], v[198:201], v[126:129]
	v_mfma_f32_16x16x32_bf16 v[122:125], v[138:141], v[194:197], v[122:125]
	v_mfma_f32_16x16x32_bf16 v[122:125], v[142:145], v[198:201], v[122:125]
	v_mfma_f32_16x16x32_bf16 v[110:113], v[130:133], v[202:205], v[110:113]
	v_mfma_f32_16x16x32_bf16 v[110:113], v[134:137], v[206:209], v[110:113]
	v_mfma_f32_16x16x32_bf16 v[106:109], v[138:141], v[202:205], v[106:109]
	v_mfma_f32_16x16x32_bf16 v[106:109], v[142:145], v[206:209], v[106:109]
	v_mfma_f32_16x16x32_bf16 v[94:97], v[130:133], v[210:213], v[94:97]
	v_mfma_f32_16x16x32_bf16 v[94:97], v[134:137], v[214:217], v[94:97]
	v_mfma_f32_16x16x32_bf16 v[90:93], v[138:141], v[210:213], v[90:93]
	v_mfma_f32_16x16x32_bf16 v[90:93], v[142:145], v[214:217], v[90:93]
	v_mfma_f32_16x16x32_bf16 v[78:81], v[130:133], v[218:221], v[78:81]
	v_mfma_f32_16x16x32_bf16 v[78:81], v[134:137], v[222:225], v[78:81]
	v_mfma_f32_16x16x32_bf16 v[74:77], v[138:141], v[218:221], v[74:77]
	v_mfma_f32_16x16x32_bf16 v[74:77], v[142:145], v[222:225], v[74:77]
	s_setprio 0
	s_setprio 1
	v_mfma_f32_16x16x32_bf16 v[118:121], v[166:169], v[194:197], v[118:121]
	v_mfma_f32_16x16x32_bf16 v[118:121], v[170:173], v[198:201], v[118:121]
	v_mfma_f32_16x16x32_bf16 v[114:117], v[186:189], v[194:197], v[114:117]
	v_mfma_f32_16x16x32_bf16 v[114:117], v[190:193], v[198:201], v[114:117]
	v_mfma_f32_16x16x32_bf16 v[102:105], v[166:169], v[202:205], v[102:105]
	v_mfma_f32_16x16x32_bf16 v[102:105], v[170:173], v[206:209], v[102:105]
	v_mfma_f32_16x16x32_bf16 v[98:101], v[186:189], v[202:205], v[98:101]
	v_mfma_f32_16x16x32_bf16 v[98:101], v[190:193], v[206:209], v[98:101]
	v_mfma_f32_16x16x32_bf16 v[86:89], v[166:169], v[210:213], v[86:89]
	v_mfma_f32_16x16x32_bf16 v[86:89], v[170:173], v[214:217], v[86:89]
	v_mfma_f32_16x16x32_bf16 v[82:85], v[186:189], v[210:213], v[82:85]
	v_mfma_f32_16x16x32_bf16 v[82:85], v[190:193], v[214:217], v[82:85]
	v_mfma_f32_16x16x32_bf16 v[70:73], v[166:169], v[218:221], v[70:73]
	v_mfma_f32_16x16x32_bf16 v[70:73], v[170:173], v[222:225], v[70:73]
	v_mfma_f32_16x16x32_bf16 v[66:69], v[186:189], v[218:221], v[66:69]
	v_mfma_f32_16x16x32_bf16 v[66:69], v[190:193], v[222:225], v[66:69]
	s_setprio 0
	s_barrier
	s_add_i32 s74, s76, s3
	v_lshl_add_u64 v[180:181], v[180:181], 0, s[38:39]
	s_mov_b32 m0, s74
	ds_read_b128 v[194:197], v177 offset:49152
	ds_read_b128 v[198:201], v177 offset:50176
	ds_read_b128 v[202:205], v177 offset:51200
	ds_read_b128 v[206:209], v177 offset:52224
	ds_read_b128 v[210:213], v177 offset:53248
	ds_read_b128 v[214:217], v177 offset:54272
	ds_read_b128 v[218:221], v177 offset:55296
	ds_read_b128 v[222:225], v177 offset:56320
	global_load_lds_dwordx4 v[180:181], off
	s_add_i32 m0, s74, 0x2000
	s_add_u32 s74, s82, 0x100080
	v_lshl_add_u64 v[180:181], v[226:227], 0, s[38:39]
	s_addc_u32 s75, s83, 0
	s_add_i32 s76, s77, s3
	global_load_lds_dwordx4 v[180:181], off
	v_lshl_add_u64 v[180:181], s[74:75], 0, v[148:149]
	s_mov_b32 m0, s76
	s_nop 0
	global_load_lds_dwordx4 v[180:181], off
	v_lshl_add_u64 v[180:181], s[74:75], 0, v[152:153]
	s_add_i32 m0, s76, 0x2000
	s_nop 0
	global_load_lds_dwordx4 v[180:181], off
	v_lshl_add_u64 v[180:181], v[228:229], 0, s[38:39]
	s_mov_b32 m0, s62
	s_nop 0
	global_load_lds_dwordx4 v[180:181], off
	v_lshl_add_u64 v[180:181], v[230:231], 0, s[38:39]
	s_mov_b32 m0, s63
	s_nop 0
	global_load_lds_dwordx4 v[180:181], off
	s_waitcnt vmcnt(8)
	s_waitcnt lgkmcnt(0)
	s_barrier
	s_setprio 1
	s_waitcnt lgkmcnt(0)
	v_mfma_f32_16x16x32_bf16 v[62:65], v[130:133], v[194:197], v[62:65]
	v_mfma_f32_16x16x32_bf16 v[62:65], v[134:137], v[198:201], v[62:65]
	v_mfma_f32_16x16x32_bf16 v[58:61], v[138:141], v[194:197], v[58:61]
	v_mfma_f32_16x16x32_bf16 v[58:61], v[142:145], v[198:201], v[58:61]
	v_mfma_f32_16x16x32_bf16 v[46:49], v[130:133], v[202:205], v[46:49]
	v_mfma_f32_16x16x32_bf16 v[46:49], v[134:137], v[206:209], v[46:49]
	v_mfma_f32_16x16x32_bf16 v[42:45], v[138:141], v[202:205], v[42:45]
	v_mfma_f32_16x16x32_bf16 v[42:45], v[142:145], v[206:209], v[42:45]
	v_mfma_f32_16x16x32_bf16 v[30:33], v[130:133], v[210:213], v[30:33]
	v_mfma_f32_16x16x32_bf16 v[30:33], v[134:137], v[214:217], v[30:33]
	v_mfma_f32_16x16x32_bf16 v[26:29], v[138:141], v[210:213], v[26:29]
	v_mfma_f32_16x16x32_bf16 v[26:29], v[142:145], v[214:217], v[26:29]
	v_mfma_f32_16x16x32_bf16 v[14:17], v[130:133], v[218:221], v[14:17]
	v_mfma_f32_16x16x32_bf16 v[14:17], v[134:137], v[222:225], v[14:17]
	v_mfma_f32_16x16x32_bf16 v[10:13], v[138:141], v[218:221], v[10:13]
	v_mfma_f32_16x16x32_bf16 v[10:13], v[142:145], v[222:225], v[10:13]
	s_setprio 0
	s_setprio 1
	v_mfma_f32_16x16x32_bf16 v[54:57], v[166:169], v[194:197], v[54:57]
	v_mfma_f32_16x16x32_bf16 v[54:57], v[170:173], v[198:201], v[54:57]
	v_mfma_f32_16x16x32_bf16 v[50:53], v[186:189], v[194:197], v[50:53]
	v_mfma_f32_16x16x32_bf16 v[50:53], v[190:193], v[198:201], v[50:53]
	v_mfma_f32_16x16x32_bf16 v[38:41], v[166:169], v[202:205], v[38:41]
	v_mfma_f32_16x16x32_bf16 v[38:41], v[170:173], v[206:209], v[38:41]
	v_mfma_f32_16x16x32_bf16 v[34:37], v[186:189], v[202:205], v[34:37]
	v_mfma_f32_16x16x32_bf16 v[34:37], v[190:193], v[206:209], v[34:37]
	v_mfma_f32_16x16x32_bf16 v[22:25], v[166:169], v[210:213], v[22:25]
	v_mfma_f32_16x16x32_bf16 v[22:25], v[170:173], v[214:217], v[22:25]
	v_mfma_f32_16x16x32_bf16 v[18:21], v[186:189], v[210:213], v[18:21]
	v_mfma_f32_16x16x32_bf16 v[18:21], v[190:193], v[214:217], v[18:21]
	v_mfma_f32_16x16x32_bf16 v[6:9], v[166:169], v[218:221], v[6:9]
	v_mfma_f32_16x16x32_bf16 v[6:9], v[170:173], v[222:225], v[6:9]
	v_mfma_f32_16x16x32_bf16 v[2:5], v[186:189], v[218:221], v[2:5]
	v_mfma_f32_16x16x32_bf16 v[2:5], v[190:193], v[222:225], v[2:5]
	s_setprio 0
	s_barrier
	s_add_i32 s73, s73, 2
	s_add_u32 s50, s50, 0x100
	s_addc_u32 s51, s51, 0
	s_add_u32 s71, s71, 0x100
	s_addc_u32 s72, s72, 0
	s_cmp_gt_u32 s73, 61
	s_cbranch_scc0 .LBB0_2109
	s_and_b64 vcc, exec, s[40:41]
	s_cbranch_vccz .LBB0_2112
	s_barrier

.LBB0_2212:
	ds_read_b128 v[150:153], v162
	ds_read_b128 v[168:171], v162 offset:1024
	ds_read_b128 v[172:175], v162 offset:2048
	ds_read_b128 v[176:179], v162 offset:3072
	ds_read_b128 v[186:189], v163
	ds_read_b128 v[190:193], v163 offset:1024
	ds_read_b128 v[194:197], v163 offset:2048
	ds_read_b128 v[198:201], v163 offset:3072
	s_add_u32 s50, s6, 0xfff00080
	s_addc_u32 s51, s7, -1
	s_cmp_eq_u32 s79, 60
	s_cselect_b32 s81, s45, s51
	s_cselect_b32 s80, s75, s50
	s_cselect_b32 s51, s43, s78
	s_cselect_b32 s50, s76, s77
	v_lshl_add_u64 v[154:155], s[6:7], 0, v[142:143]
	s_add_i32 m0, s33, 0xc000
	ds_read_b128 v[202:205], v164
	ds_read_b128 v[206:209], v164 offset:1024
	ds_read_b128 v[210:213], v164 offset:2048
	ds_read_b128 v[214:217], v164 offset:3072
	ds_read_b128 v[218:221], v164 offset:4096
	ds_read_b128 v[222:225], v164 offset:5120
	ds_read_b128 v[226:229], v164 offset:6144
	ds_read_b128 v[230:233], v164 offset:7168
	global_load_lds_dwordx4 v[154:155], off
	v_lshl_add_u64 v[154:155], s[6:7], 0, v[144:145]
	s_add_i32 m0, s33, 0xe000
	s_nop 0
	global_load_lds_dwordx4 v[154:155], off
	s_waitcnt vmcnt(8)
	s_waitcnt lgkmcnt(0)
	s_barrier
	s_setprio 1
	s_waitcnt lgkmcnt(0)
	v_mfma_f32_16x16x32_bf16 v[126:129], v[150:153], v[202:205], v[126:129]
	v_mfma_f32_16x16x32_bf16 v[126:129], v[168:171], v[206:209], v[126:129]
	v_mfma_f32_16x16x32_bf16 v[118:121], v[172:175], v[202:205], v[118:121]
	v_mfma_f32_16x16x32_bf16 v[118:121], v[176:179], v[206:209], v[118:121]
	v_mfma_f32_16x16x32_bf16 v[110:113], v[150:153], v[210:213], v[110:113]
	v_mfma_f32_16x16x32_bf16 v[110:113], v[168:171], v[214:217], v[110:113]
	v_mfma_f32_16x16x32_bf16 v[102:105], v[172:175], v[210:213], v[102:105]
	v_mfma_f32_16x16x32_bf16 v[102:105], v[176:179], v[214:217], v[102:105]
	v_mfma_f32_16x16x32_bf16 v[94:97], v[150:153], v[218:221], v[94:97]
	v_mfma_f32_16x16x32_bf16 v[94:97], v[168:171], v[222:225], v[94:97]
	v_mfma_f32_16x16x32_bf16 v[86:89], v[172:175], v[218:221], v[86:89]
	v_mfma_f32_16x16x32_bf16 v[86:89], v[176:179], v[222:225], v[86:89]
	v_mfma_f32_16x16x32_bf16 v[78:81], v[150:153], v[226:229], v[78:81]
	v_mfma_f32_16x16x32_bf16 v[78:81], v[168:171], v[230:233], v[78:81]
	v_mfma_f32_16x16x32_bf16 v[70:73], v[172:175], v[226:229], v[70:73]
	v_mfma_f32_16x16x32_bf16 v[70:73], v[176:179], v[230:233], v[70:73]
	s_setprio 0
	s_setprio 1
	v_mfma_f32_16x16x32_bf16 v[122:125], v[186:189], v[202:205], v[122:125]
	v_mfma_f32_16x16x32_bf16 v[122:125], v[190:193], v[206:209], v[122:125]
	v_mfma_f32_16x16x32_bf16 v[114:117], v[194:197], v[202:205], v[114:117]
	v_mfma_f32_16x16x32_bf16 v[114:117], v[198:201], v[206:209], v[114:117]
	v_mfma_f32_16x16x32_bf16 v[106:109], v[186:189], v[210:213], v[106:109]
	v_mfma_f32_16x16x32_bf16 v[106:109], v[190:193], v[214:217], v[106:109]
	v_mfma_f32_16x16x32_bf16 v[98:101], v[194:197], v[210:213], v[98:101]
	v_mfma_f32_16x16x32_bf16 v[98:101], v[198:201], v[214:217], v[98:101]
	v_mfma_f32_16x16x32_bf16 v[90:93], v[186:189], v[218:221], v[90:93]
	v_mfma_f32_16x16x32_bf16 v[90:93], v[190:193], v[222:225], v[90:93]
	v_mfma_f32_16x16x32_bf16 v[82:85], v[194:197], v[218:221], v[82:85]
	v_mfma_f32_16x16x32_bf16 v[82:85], v[198:201], v[222:225], v[82:85]
	v_mfma_f32_16x16x32_bf16 v[74:77], v[186:189], v[226:229], v[74:77]
	v_mfma_f32_16x16x32_bf16 v[74:77], v[190:193], v[230:233], v[74:77]
	v_mfma_f32_16x16x32_bf16 v[66:69], v[194:197], v[226:229], v[66:69]
	v_mfma_f32_16x16x32_bf16 v[66:69], v[198:201], v[230:233], v[66:69]
	s_setprio 0
	s_barrier
	s_add_i32 s82, s68, s29
	v_lshl_add_u64 v[154:155], s[50:51], 0, v[134:135]
	s_mov_b32 m0, s82
	ds_read_b128 v[202:205], v164 offset:16384
	ds_read_b128 v[206:209], v164 offset:17408
	ds_read_b128 v[210:213], v164 offset:18432
	ds_read_b128 v[214:217], v164 offset:19456
	ds_read_b128 v[218:221], v164 offset:20480
	ds_read_b128 v[222:225], v164 offset:21504
	ds_read_b128 v[226:229], v164 offset:22528
	ds_read_b128 v[230:233], v164 offset:23552
	global_load_lds_dwordx4 v[154:155], off
	s_add_i32 m0, s82, 0x2000
	s_add_u32 s82, s50, 0x100000
	v_lshl_add_u64 v[180:181], s[50:51], 0, v[138:139]
	s_addc_u32 s83, s51, 0
	s_add_i32 s84, s69, s29
	global_load_lds_dwordx4 v[180:181], off
	v_lshl_add_u64 v[234:235], s[82:83], 0, v[134:135]
	s_mov_b32 m0, s84
	v_lshl_add_u64 v[236:237], s[80:81], 0, v[136:137]
	global_load_lds_dwordx4 v[234:235], off
	v_lshl_add_u64 v[234:235], s[82:83], 0, v[138:139]
	s_add_i32 m0, s84, 0x2000
	s_nop 0
	global_load_lds_dwordx4 v[234:235], off
	v_lshl_add_u64 v[234:235], s[80:81], 0, v[132:133]
	s_mov_b32 m0, s33
	s_nop 0
	global_load_lds_dwordx4 v[234:235], off
	s_mov_b32 m0, s35
	s_nop 0
	global_load_lds_dwordx4 v[236:237], off
	s_waitcnt vmcnt(8)
	s_waitcnt lgkmcnt(0)
	s_barrier
	s_setprio 1
	s_waitcnt lgkmcnt(0)
	v_mfma_f32_16x16x32_bf16 v[62:65], v[150:153], v[202:205], v[62:65]
	v_mfma_f32_16x16x32_bf16 v[62:65], v[168:171], v[206:209], v[62:65]
	v_mfma_f32_16x16x32_bf16 v[54:57], v[172:175], v[202:205], v[54:57]
	v_mfma_f32_16x16x32_bf16 v[54:57], v[176:179], v[206:209], v[54:57]
	v_mfma_f32_16x16x32_bf16 v[46:49], v[150:153], v[210:213], v[46:49]
	v_mfma_f32_16x16x32_bf16 v[46:49], v[168:171], v[214:217], v[46:49]
	v_mfma_f32_16x16x32_bf16 v[38:41], v[172:175], v[210:213], v[38:41]
	v_mfma_f32_16x16x32_bf16 v[38:41], v[176:179], v[214:217], v[38:41]
	v_mfma_f32_16x16x32_bf16 v[30:33], v[150:153], v[218:221], v[30:33]
	v_mfma_f32_16x16x32_bf16 v[30:33], v[168:171], v[222:225], v[30:33]
	v_mfma_f32_16x16x32_bf16 v[22:25], v[172:175], v[218:221], v[22:25]
	v_mfma_f32_16x16x32_bf16 v[22:25], v[176:179], v[222:225], v[22:25]
	v_mfma_f32_16x16x32_bf16 v[14:17], v[150:153], v[226:229], v[14:17]
	v_mfma_f32_16x16x32_bf16 v[14:17], v[168:171], v[230:233], v[14:17]
	v_mfma_f32_16x16x32_bf16 v[6:9], v[172:175], v[226:229], v[6:9]
	v_mfma_f32_16x16x32_bf16 v[6:9], v[176:179], v[230:233], v[6:9]
	s_setprio 0
	s_setprio 1
	v_mfma_f32_16x16x32_bf16 v[58:61], v[186:189], v[202:205], v[58:61]
	v_mfma_f32_16x16x32_bf16 v[58:61], v[190:193], v[206:209], v[58:61]
	v_mfma_f32_16x16x32_bf16 v[50:53], v[194:197], v[202:205], v[50:53]
	v_mfma_f32_16x16x32_bf16 v[50:53], v[198:201], v[206:209], v[50:53]
	v_mfma_f32_16x16x32_bf16 v[42:45], v[186:189], v[210:213], v[42:45]
	v_mfma_f32_16x16x32_bf16 v[42:45], v[190:193], v[214:217], v[42:45]
	v_mfma_f32_16x16x32_bf16 v[34:37], v[194:197], v[210:213], v[34:37]
	v_mfma_f32_16x16x32_bf16 v[34:37], v[198:201], v[214:217], v[34:37]
	v_mfma_f32_16x16x32_bf16 v[26:29], v[186:189], v[218:221], v[26:29]
	v_mfma_f32_16x16x32_bf16 v[26:29], v[190:193], v[222:225], v[26:29]
	v_mfma_f32_16x16x32_bf16 v[18:21], v[194:197], v[218:221], v[18:21]
	v_mfma_f32_16x16x32_bf16 v[18:21], v[198:201], v[222:225], v[18:21]
	v_mfma_f32_16x16x32_bf16 v[10:13], v[186:189], v[226:229], v[10:13]
	v_mfma_f32_16x16x32_bf16 v[10:13], v[190:193], v[230:233], v[10:13]
	v_mfma_f32_16x16x32_bf16 v[2:5], v[194:197], v[226:229], v[2:5]
	v_mfma_f32_16x16x32_bf16 v[2:5], v[198:201], v[230:233], v[2:5]
	s_setprio 0
	s_barrier
	s_add_i32 s82, 0, 0x18000
	v_add_u32_e32 v140, s82, v158
	s_add_i32 s83, 0, 0x1c000
	ds_read_b128 v[150:153], v140
	ds_read_b128 v[168:171], v140 offset:1024
	ds_read_b128 v[172:175], v140 offset:2048
	ds_read_b128 v[176:179], v140 offset:3072
	v_add_u32_e32 v140, s83, v158
	ds_read_b128 v[186:189], v140
	ds_read_b128 v[190:193], v140 offset:1024
	ds_read_b128 v[194:197], v140 offset:2048
	ds_read_b128 v[198:201], v140 offset:3072
	s_add_u32 s80, s80, 0x100000
	s_addc_u32 s81, s81, 0
	s_mov_b32 m0, s59
	v_lshl_add_u64 v[238:239], s[80:81], 0, v[132:133]
	ds_read_b128 v[202:205], v164 offset:32768
	ds_read_b128 v[206:209], v164 offset:33792
	ds_read_b128 v[210:213], v164 offset:34816
	ds_read_b128 v[214:217], v164 offset:35840
	ds_read_b128 v[218:221], v164 offset:36864
	ds_read_b128 v[222:225], v164 offset:37888
	ds_read_b128 v[226:229], v164 offset:38912
	ds_read_b128 v[230:233], v164 offset:39936
	global_load_lds_dwordx4 v[238:239], off
	v_lshl_add_u64 v[238:239], s[80:81], 0, v[136:137]
	s_mov_b32 m0, s62
	s_nop 0
	global_load_lds_dwordx4 v[238:239], off
	s_waitcnt vmcnt(8)
	s_waitcnt lgkmcnt(0)
	s_barrier
	s_setprio 1
	s_waitcnt lgkmcnt(0)
	v_mfma_f32_16x16x32_bf16 v[126:129], v[150:153], v[202:205], v[126:129]
	v_mfma_f32_16x16x32_bf16 v[126:129], v[168:171], v[206:209], v[126:129]
	v_mfma_f32_16x16x32_bf16 v[118:121], v[172:175], v[202:205], v[118:121]
	v_mfma_f32_16x16x32_bf16 v[118:121], v[176:179], v[206:209], v[118:121]
	v_mfma_f32_16x16x32_bf16 v[110:113], v[150:153], v[210:213], v[110:113]
	v_mfma_f32_16x16x32_bf16 v[110:113], v[168:171], v[214:217], v[110:113]
	v_mfma_f32_16x16x32_bf16 v[102:105], v[172:175], v[210:213], v[102:105]
	v_mfma_f32_16x16x32_bf16 v[102:105], v[176:179], v[214:217], v[102:105]
	v_mfma_f32_16x16x32_bf16 v[94:97], v[150:153], v[218:221], v[94:97]
	v_mfma_f32_16x16x32_bf16 v[94:97], v[168:171], v[222:225], v[94:97]
	v_mfma_f32_16x16x32_bf16 v[86:89], v[172:175], v[218:221], v[86:89]
	v_mfma_f32_16x16x32_bf16 v[86:89], v[176:179], v[222:225], v[86:89]
	v_mfma_f32_16x16x32_bf16 v[78:81], v[150:153], v[226:229], v[78:81]
	v_mfma_f32_16x16x32_bf16 v[78:81], v[168:171], v[230:233], v[78:81]
	v_mfma_f32_16x16x32_bf16 v[70:73], v[172:175], v[226:229], v[70:73]
	v_mfma_f32_16x16x32_bf16 v[70:73], v[176:179], v[230:233], v[70:73]
	s_setprio 0
	s_setprio 1
	v_mfma_f32_16x16x32_bf16 v[122:125], v[186:189], v[202:205], v[122:125]
	v_mfma_f32_16x16x32_bf16 v[122:125], v[190:193], v[206:209], v[122:125]
	v_mfma_f32_16x16x32_bf16 v[114:117], v[194:197], v[202:205], v[114:117]
	v_mfma_f32_16x16x32_bf16 v[114:117], v[198:201], v[206:209], v[114:117]
	v_mfma_f32_16x16x32_bf16 v[106:109], v[186:189], v[210:213], v[106:109]
	v_mfma_f32_16x16x32_bf16 v[106:109], v[190:193], v[214:217], v[106:109]
	v_mfma_f32_16x16x32_bf16 v[98:101], v[194:197], v[210:213], v[98:101]
	v_mfma_f32_16x16x32_bf16 v[98:101], v[198:201], v[214:217], v[98:101]
	v_mfma_f32_16x16x32_bf16 v[90:93], v[186:189], v[218:221], v[90:93]
	v_mfma_f32_16x16x32_bf16 v[90:93], v[190:193], v[222:225], v[90:93]
	v_mfma_f32_16x16x32_bf16 v[82:85], v[194:197], v[218:221], v[82:85]
	v_mfma_f32_16x16x32_bf16 v[82:85], v[198:201], v[222:225], v[82:85]
	v_mfma_f32_16x16x32_bf16 v[74:77], v[186:189], v[226:229], v[74:77]
	v_mfma_f32_16x16x32_bf16 v[74:77], v[190:193], v[230:233], v[74:77]
	v_mfma_f32_16x16x32_bf16 v[66:69], v[194:197], v[226:229], v[66:69]
	v_mfma_f32_16x16x32_bf16 v[66:69], v[198:201], v[230:233], v[66:69]
	s_setprio 0
	s_barrier
	s_add_i32 s80, s82, s29
	v_lshl_add_u64 v[154:155], v[154:155], 0, s[38:39]
	s_mov_b32 m0, s80
	ds_read_b128 v[202:205], v164 offset:49152
	ds_read_b128 v[206:209], v164 offset:50176
	ds_read_b128 v[210:213], v164 offset:51200
	ds_read_b128 v[214:217], v164 offset:52224
	ds_read_b128 v[218:221], v164 offset:53248
	ds_read_b128 v[222:225], v164 offset:54272
	ds_read_b128 v[226:229], v164 offset:55296
	ds_read_b128 v[230:233], v164 offset:56320
	global_load_lds_dwordx4 v[154:155], off
	s_add_i32 m0, s80, 0x2000
	s_add_u32 s50, s50, 0x100080
	v_lshl_add_u64 v[154:155], v[180:181], 0, s[38:39]
	s_addc_u32 s51, s51, 0
	s_add_i32 s80, s83, s29
	global_load_lds_dwordx4 v[154:155], off
	v_lshl_add_u64 v[154:155], s[50:51], 0, v[134:135]
	s_mov_b32 m0, s80
	s_nop 0
	global_load_lds_dwordx4 v[154:155], off
	v_lshl_add_u64 v[154:155], s[50:51], 0, v[138:139]
	s_add_i32 m0, s80, 0x2000
	s_nop 0
	global_load_lds_dwordx4 v[154:155], off
	v_lshl_add_u64 v[154:155], v[234:235], 0, s[38:39]
	s_mov_b32 m0, s65
	s_nop 0
	global_load_lds_dwordx4 v[154:155], off
	v_lshl_add_u64 v[154:155], v[236:237], 0, s[38:39]
	s_mov_b32 m0, s66
	s_nop 0
	global_load_lds_dwordx4 v[154:155], off
	s_waitcnt vmcnt(8)
	s_waitcnt lgkmcnt(0)
	s_barrier
	s_setprio 1
	s_waitcnt lgkmcnt(0)
	v_mfma_f32_16x16x32_bf16 v[62:65], v[150:153], v[202:205], v[62:65]
	v_mfma_f32_16x16x32_bf16 v[62:65], v[168:171], v[206:209], v[62:65]
	v_mfma_f32_16x16x32_bf16 v[54:57], v[172:175], v[202:205], v[54:57]
	v_mfma_f32_16x16x32_bf16 v[54:57], v[176:179], v[206:209], v[54:57]
	v_mfma_f32_16x16x32_bf16 v[46:49], v[150:153], v[210:213], v[46:49]
	v_mfma_f32_16x16x32_bf16 v[46:49], v[168:171], v[214:217], v[46:49]
	v_mfma_f32_16x16x32_bf16 v[38:41], v[172:175], v[210:213], v[38:41]
	v_mfma_f32_16x16x32_bf16 v[38:41], v[176:179], v[214:217], v[38:41]
	v_mfma_f32_16x16x32_bf16 v[30:33], v[150:153], v[218:221], v[30:33]
	v_mfma_f32_16x16x32_bf16 v[30:33], v[168:171], v[222:225], v[30:33]
	v_mfma_f32_16x16x32_bf16 v[22:25], v[172:175], v[218:221], v[22:25]
	v_mfma_f32_16x16x32_bf16 v[22:25], v[176:179], v[222:225], v[22:25]
	v_mfma_f32_16x16x32_bf16 v[14:17], v[150:153], v[226:229], v[14:17]
	v_mfma_f32_16x16x32_bf16 v[14:17], v[168:171], v[230:233], v[14:17]
	v_mfma_f32_16x16x32_bf16 v[6:9], v[172:175], v[226:229], v[6:9]
	v_mfma_f32_16x16x32_bf16 v[6:9], v[176:179], v[230:233], v[6:9]
	s_setprio 0
	s_setprio 1
	v_mfma_f32_16x16x32_bf16 v[58:61], v[186:189], v[202:205], v[58:61]
	v_mfma_f32_16x16x32_bf16 v[58:61], v[190:193], v[206:209], v[58:61]
	v_mfma_f32_16x16x32_bf16 v[50:53], v[194:197], v[202:205], v[50:53]
	v_mfma_f32_16x16x32_bf16 v[50:53], v[198:201], v[206:209], v[50:53]
	v_mfma_f32_16x16x32_bf16 v[42:45], v[186:189], v[210:213], v[42:45]
	v_mfma_f32_16x16x32_bf16 v[42:45], v[190:193], v[214:217], v[42:45]
	v_mfma_f32_16x16x32_bf16 v[34:37], v[194:197], v[210:213], v[34:37]
	v_mfma_f32_16x16x32_bf16 v[34:37], v[198:201], v[214:217], v[34:37]
	v_mfma_f32_16x16x32_bf16 v[26:29], v[186:189], v[218:221], v[26:29]
	v_mfma_f32_16x16x32_bf16 v[26:29], v[190:193], v[222:225], v[26:29]
	v_mfma_f32_16x16x32_bf16 v[18:21], v[194:197], v[218:221], v[18:21]
	v_mfma_f32_16x16x32_bf16 v[18:21], v[198:201], v[222:225], v[18:21]
	v_mfma_f32_16x16x32_bf16 v[10:13], v[186:189], v[226:229], v[10:13]
	v_mfma_f32_16x16x32_bf16 v[10:13], v[190:193], v[230:233], v[10:13]
	v_mfma_f32_16x16x32_bf16 v[2:5], v[194:197], v[226:229], v[2:5]
	v_mfma_f32_16x16x32_bf16 v[2:5], v[198:201], v[230:233], v[2:5]
	s_setprio 0
	s_barrier
	s_add_i32 s79, s79, 2
	s_add_u32 s6, s6, 0x100
	s_addc_u32 s7, s7, 0
	s_add_u32 s77, s77, 0x100
	s_addc_u32 s78, s78, 0
	s_cmp_gt_u32 s79, 61
	s_cbranch_scc0 .LBB0_2212
	s_and_b64 vcc, exec, s[40:41]
	s_cbranch_vccz .LBB0_2215
	s_barrier

.LBB0_2340:
	ds_read_b128 v[130:133], v163
	ds_read_b128 v[134:137], v163 offset:1024
	ds_read_b128 v[138:141], v163 offset:2048
	ds_read_b128 v[142:145], v163 offset:3072
	ds_read_b128 v[146:149], v190
	ds_read_b128 v[150:153], v190 offset:1024
	ds_read_b128 v[174:177], v190 offset:2048
	ds_read_b128 v[178:181], v190 offset:3072
	s_add_u32 s42, s40, 0xffd50080
	s_addc_u32 s43, s41, -1
	s_cmpk_eq_i32 s71, 0xa8
	s_cselect_b32 s45, s1, s43
	s_cselect_b32 s44, s0, s42
	s_cselect_b32 s43, s39, s70
	s_cselect_b32 s42, s38, s12
	v_lshl_add_u64 v[222:223], s[40:41], 0, v[166:167]
	s_add_i32 m0, s46, 0xc000
	ds_read_b128 v[186:189], v191
	ds_read_b128 v[194:197], v191 offset:1024
	ds_read_b128 v[198:201], v191 offset:2048
	ds_read_b128 v[202:205], v191 offset:3072
	ds_read_b128 v[206:209], v191 offset:4096
	ds_read_b128 v[210:213], v191 offset:5120
	ds_read_b128 v[214:217], v191 offset:6144
	ds_read_b128 v[218:221], v191 offset:7168
	global_load_lds_dwordx4 v[222:223], off
	v_lshl_add_u64 v[222:223], s[40:41], 0, v[168:169]
	s_add_i32 m0, s46, 0xe000
	s_nop 0
	global_load_lds_dwordx4 v[222:223], off
	s_waitcnt vmcnt(8)
	s_waitcnt lgkmcnt(0)
	s_barrier
	s_setprio 1
	s_waitcnt lgkmcnt(0)
	v_mfma_f32_16x16x32_bf16 v[126:129], v[130:133], v[186:189], v[126:129]
	v_mfma_f32_16x16x32_bf16 v[126:129], v[134:137], v[194:197], v[126:129]
	v_mfma_f32_16x16x32_bf16 v[122:125], v[138:141], v[186:189], v[122:125]
	v_mfma_f32_16x16x32_bf16 v[122:125], v[142:145], v[194:197], v[122:125]
	v_mfma_f32_16x16x32_bf16 v[110:113], v[130:133], v[198:201], v[110:113]
	v_mfma_f32_16x16x32_bf16 v[110:113], v[134:137], v[202:205], v[110:113]
	v_mfma_f32_16x16x32_bf16 v[106:109], v[138:141], v[198:201], v[106:109]
	v_mfma_f32_16x16x32_bf16 v[106:109], v[142:145], v[202:205], v[106:109]
	v_mfma_f32_16x16x32_bf16 v[94:97], v[130:133], v[206:209], v[94:97]
	v_mfma_f32_16x16x32_bf16 v[94:97], v[134:137], v[210:213], v[94:97]
	v_mfma_f32_16x16x32_bf16 v[90:93], v[138:141], v[206:209], v[90:93]
	v_mfma_f32_16x16x32_bf16 v[90:93], v[142:145], v[210:213], v[90:93]
	v_mfma_f32_16x16x32_bf16 v[78:81], v[130:133], v[214:217], v[78:81]
	v_mfma_f32_16x16x32_bf16 v[78:81], v[134:137], v[218:221], v[78:81]
	v_mfma_f32_16x16x32_bf16 v[74:77], v[138:141], v[214:217], v[74:77]
	v_mfma_f32_16x16x32_bf16 v[74:77], v[142:145], v[218:221], v[74:77]
	s_setprio 0
	s_setprio 1
	v_mfma_f32_16x16x32_bf16 v[118:121], v[146:149], v[186:189], v[118:121]
	v_mfma_f32_16x16x32_bf16 v[118:121], v[150:153], v[194:197], v[118:121]
	v_mfma_f32_16x16x32_bf16 v[114:117], v[174:177], v[186:189], v[114:117]
	v_mfma_f32_16x16x32_bf16 v[114:117], v[178:181], v[194:197], v[114:117]
	v_mfma_f32_16x16x32_bf16 v[102:105], v[146:149], v[198:201], v[102:105]
	v_mfma_f32_16x16x32_bf16 v[102:105], v[150:153], v[202:205], v[102:105]
	v_mfma_f32_16x16x32_bf16 v[98:101], v[174:177], v[198:201], v[98:101]
	v_mfma_f32_16x16x32_bf16 v[98:101], v[178:181], v[202:205], v[98:101]
	v_mfma_f32_16x16x32_bf16 v[86:89], v[146:149], v[206:209], v[86:89]
	v_mfma_f32_16x16x32_bf16 v[86:89], v[150:153], v[210:213], v[86:89]
	v_mfma_f32_16x16x32_bf16 v[82:85], v[174:177], v[206:209], v[82:85]
	v_mfma_f32_16x16x32_bf16 v[82:85], v[178:181], v[210:213], v[82:85]
	v_mfma_f32_16x16x32_bf16 v[70:73], v[146:149], v[214:217], v[70:73]
	v_mfma_f32_16x16x32_bf16 v[70:73], v[150:153], v[218:221], v[70:73]
	v_mfma_f32_16x16x32_bf16 v[66:69], v[174:177], v[214:217], v[66:69]
	v_mfma_f32_16x16x32_bf16 v[66:69], v[178:181], v[218:221], v[66:69]
	s_setprio 0
	s_barrier
	s_add_i32 s72, s65, s35
	v_lshl_add_u64 v[222:223], s[42:43], 0, v[156:157]
	s_mov_b32 m0, s72
	ds_read_b128 v[186:189], v191 offset:16384
	ds_read_b128 v[194:197], v191 offset:17408
	ds_read_b128 v[198:201], v191 offset:18432
	ds_read_b128 v[202:205], v191 offset:19456
	ds_read_b128 v[206:209], v191 offset:20480
	ds_read_b128 v[210:213], v191 offset:21504
	ds_read_b128 v[214:217], v191 offset:22528
	ds_read_b128 v[218:221], v191 offset:23552
	global_load_lds_dwordx4 v[222:223], off
	s_add_i32 m0, s72, 0x2000
	s_add_u32 s72, s42, 0x2b0000
	v_lshl_add_u64 v[224:225], s[42:43], 0, v[160:161]
	s_addc_u32 s73, s43, 0
	s_add_i32 s74, s66, s35
	global_load_lds_dwordx4 v[224:225], off
	v_lshl_add_u64 v[226:227], s[72:73], 0, v[156:157]
	s_mov_b32 m0, s74
	v_lshl_add_u64 v[228:229], s[44:45], 0, v[158:159]
	global_load_lds_dwordx4 v[226:227], off
	v_lshl_add_u64 v[226:227], s[72:73], 0, v[160:161]
	s_add_i32 m0, s74, 0x2000
	s_nop 0
	global_load_lds_dwordx4 v[226:227], off
	v_lshl_add_u64 v[226:227], s[44:45], 0, v[154:155]
	s_mov_b32 m0, s46
	s_nop 0
	global_load_lds_dwordx4 v[226:227], off
	s_mov_b32 m0, s47
	s_nop 0
	global_load_lds_dwordx4 v[228:229], off
	s_waitcnt vmcnt(8)
	s_waitcnt lgkmcnt(0)
	s_barrier
	s_setprio 1
	s_waitcnt lgkmcnt(0)
	v_mfma_f32_16x16x32_bf16 v[62:65], v[130:133], v[186:189], v[62:65]
	v_mfma_f32_16x16x32_bf16 v[62:65], v[134:137], v[194:197], v[62:65]
	v_mfma_f32_16x16x32_bf16 v[58:61], v[138:141], v[186:189], v[58:61]
	v_mfma_f32_16x16x32_bf16 v[58:61], v[142:145], v[194:197], v[58:61]
	v_mfma_f32_16x16x32_bf16 v[46:49], v[130:133], v[198:201], v[46:49]
	v_mfma_f32_16x16x32_bf16 v[46:49], v[134:137], v[202:205], v[46:49]
	v_mfma_f32_16x16x32_bf16 v[42:45], v[138:141], v[198:201], v[42:45]
	v_mfma_f32_16x16x32_bf16 v[42:45], v[142:145], v[202:205], v[42:45]
	v_mfma_f32_16x16x32_bf16 v[30:33], v[130:133], v[206:209], v[30:33]
	v_mfma_f32_16x16x32_bf16 v[30:33], v[134:137], v[210:213], v[30:33]
	v_mfma_f32_16x16x32_bf16 v[26:29], v[138:141], v[206:209], v[26:29]
	v_mfma_f32_16x16x32_bf16 v[26:29], v[142:145], v[210:213], v[26:29]
	v_mfma_f32_16x16x32_bf16 v[14:17], v[130:133], v[214:217], v[14:17]
	v_mfma_f32_16x16x32_bf16 v[14:17], v[134:137], v[218:221], v[14:17]
	v_mfma_f32_16x16x32_bf16 v[10:13], v[138:141], v[214:217], v[10:13]
	v_mfma_f32_16x16x32_bf16 v[10:13], v[142:145], v[218:221], v[10:13]
	s_setprio 0
	s_setprio 1
	v_mfma_f32_16x16x32_bf16 v[54:57], v[146:149], v[186:189], v[54:57]
	v_mfma_f32_16x16x32_bf16 v[54:57], v[150:153], v[194:197], v[54:57]
	v_mfma_f32_16x16x32_bf16 v[50:53], v[174:177], v[186:189], v[50:53]
	v_mfma_f32_16x16x32_bf16 v[50:53], v[178:181], v[194:197], v[50:53]
	v_mfma_f32_16x16x32_bf16 v[38:41], v[146:149], v[198:201], v[38:41]
	v_mfma_f32_16x16x32_bf16 v[38:41], v[150:153], v[202:205], v[38:41]
	v_mfma_f32_16x16x32_bf16 v[34:37], v[174:177], v[198:201], v[34:37]
	v_mfma_f32_16x16x32_bf16 v[34:37], v[178:181], v[202:205], v[34:37]
	v_mfma_f32_16x16x32_bf16 v[22:25], v[146:149], v[206:209], v[22:25]
	v_mfma_f32_16x16x32_bf16 v[22:25], v[150:153], v[210:213], v[22:25]
	v_mfma_f32_16x16x32_bf16 v[18:21], v[174:177], v[206:209], v[18:21]
	v_mfma_f32_16x16x32_bf16 v[18:21], v[178:181], v[210:213], v[18:21]
	v_mfma_f32_16x16x32_bf16 v[6:9], v[146:149], v[214:217], v[6:9]
	v_mfma_f32_16x16x32_bf16 v[6:9], v[150:153], v[218:221], v[6:9]
	v_mfma_f32_16x16x32_bf16 v[2:5], v[174:177], v[214:217], v[2:5]
	v_mfma_f32_16x16x32_bf16 v[2:5], v[178:181], v[218:221], v[2:5]
	s_setprio 0
	s_barrier
	s_add_i32 s72, 0, 0x18000
	s_add_i32 s73, 0, 0x1c000
	v_add_u32_e32 v142, s72, v183
	v_add_u32_e32 v178, s73, v183
	ds_read_b128 v[130:133], v142
	ds_read_b128 v[134:137], v142 offset:1024
	ds_read_b128 v[138:141], v142 offset:2048
	ds_read_b128 v[142:145], v142 offset:3072
	ds_read_b128 v[146:149], v178
	ds_read_b128 v[150:153], v178 offset:1024
	ds_read_b128 v[174:177], v178 offset:2048
	ds_read_b128 v[178:181], v178 offset:3072
	s_add_u32 s44, s44, 0x2b0000
	s_addc_u32 s45, s45, 0
	s_mov_b32 m0, s48
	v_lshl_add_u64 v[230:231], s[44:45], 0, v[154:155]
	ds_read_b128 v[186:189], v191 offset:32768
	ds_read_b128 v[194:197], v191 offset:33792
	ds_read_b128 v[198:201], v191 offset:34816
	ds_read_b128 v[202:205], v191 offset:35840
	ds_read_b128 v[206:209], v191 offset:36864
	ds_read_b128 v[210:213], v191 offset:37888
	ds_read_b128 v[214:217], v191 offset:38912
	ds_read_b128 v[218:221], v191 offset:39936
	global_load_lds_dwordx4 v[230:231], off
	v_lshl_add_u64 v[230:231], s[44:45], 0, v[158:159]
	s_mov_b32 m0, s49
	s_nop 0
	global_load_lds_dwordx4 v[230:231], off
	s_waitcnt vmcnt(8)
	s_waitcnt lgkmcnt(0)
	s_barrier
	s_setprio 1
	s_waitcnt lgkmcnt(0)
	v_mfma_f32_16x16x32_bf16 v[126:129], v[130:133], v[186:189], v[126:129]
	v_mfma_f32_16x16x32_bf16 v[126:129], v[134:137], v[194:197], v[126:129]
	v_mfma_f32_16x16x32_bf16 v[122:125], v[138:141], v[186:189], v[122:125]
	v_mfma_f32_16x16x32_bf16 v[122:125], v[142:145], v[194:197], v[122:125]
	v_mfma_f32_16x16x32_bf16 v[110:113], v[130:133], v[198:201], v[110:113]
	v_mfma_f32_16x16x32_bf16 v[110:113], v[134:137], v[202:205], v[110:113]
	v_mfma_f32_16x16x32_bf16 v[106:109], v[138:141], v[198:201], v[106:109]
	v_mfma_f32_16x16x32_bf16 v[106:109], v[142:145], v[202:205], v[106:109]
	v_mfma_f32_16x16x32_bf16 v[94:97], v[130:133], v[206:209], v[94:97]
	v_mfma_f32_16x16x32_bf16 v[94:97], v[134:137], v[210:213], v[94:97]
	v_mfma_f32_16x16x32_bf16 v[90:93], v[138:141], v[206:209], v[90:93]
	v_mfma_f32_16x16x32_bf16 v[90:93], v[142:145], v[210:213], v[90:93]
	v_mfma_f32_16x16x32_bf16 v[78:81], v[130:133], v[214:217], v[78:81]
	v_mfma_f32_16x16x32_bf16 v[78:81], v[134:137], v[218:221], v[78:81]
	v_mfma_f32_16x16x32_bf16 v[74:77], v[138:141], v[214:217], v[74:77]
	v_mfma_f32_16x16x32_bf16 v[74:77], v[142:145], v[218:221], v[74:77]
	s_setprio 0
	s_setprio 1
	v_mfma_f32_16x16x32_bf16 v[118:121], v[146:149], v[186:189], v[118:121]
	v_mfma_f32_16x16x32_bf16 v[118:121], v[150:153], v[194:197], v[118:121]
	v_mfma_f32_16x16x32_bf16 v[114:117], v[174:177], v[186:189], v[114:117]
	v_mfma_f32_16x16x32_bf16 v[114:117], v[178:181], v[194:197], v[114:117]
	v_mfma_f32_16x16x32_bf16 v[102:105], v[146:149], v[198:201], v[102:105]
	v_mfma_f32_16x16x32_bf16 v[102:105], v[150:153], v[202:205], v[102:105]
	v_mfma_f32_16x16x32_bf16 v[98:101], v[174:177], v[198:201], v[98:101]
	v_mfma_f32_16x16x32_bf16 v[98:101], v[178:181], v[202:205], v[98:101]
	v_mfma_f32_16x16x32_bf16 v[86:89], v[146:149], v[206:209], v[86:89]
	v_mfma_f32_16x16x32_bf16 v[86:89], v[150:153], v[210:213], v[86:89]
	v_mfma_f32_16x16x32_bf16 v[82:85], v[174:177], v[206:209], v[82:85]
	v_mfma_f32_16x16x32_bf16 v[82:85], v[178:181], v[210:213], v[82:85]
	v_mfma_f32_16x16x32_bf16 v[70:73], v[146:149], v[214:217], v[70:73]
	v_mfma_f32_16x16x32_bf16 v[70:73], v[150:153], v[218:221], v[70:73]
	v_mfma_f32_16x16x32_bf16 v[66:69], v[174:177], v[214:217], v[66:69]
	v_mfma_f32_16x16x32_bf16 v[66:69], v[178:181], v[218:221], v[66:69]
	s_setprio 0
	s_barrier
	s_add_i32 s44, s72, s35
	v_lshl_add_u64 v[222:223], v[222:223], 0, s[28:29]
	s_mov_b32 m0, s44
	ds_read_b128 v[186:189], v191 offset:49152
	ds_read_b128 v[194:197], v191 offset:50176
	ds_read_b128 v[198:201], v191 offset:51200
	ds_read_b128 v[202:205], v191 offset:52224
	ds_read_b128 v[206:209], v191 offset:53248
	ds_read_b128 v[210:213], v191 offset:54272
	ds_read_b128 v[214:217], v191 offset:55296
	ds_read_b128 v[218:221], v191 offset:56320
	global_load_lds_dwordx4 v[222:223], off
	s_add_i32 m0, s44, 0x2000
	s_add_u32 s42, s42, 0x2b0080
	v_lshl_add_u64 v[222:223], v[224:225], 0, s[28:29]
	s_addc_u32 s43, s43, 0
	s_add_i32 s44, s73, s35
	global_load_lds_dwordx4 v[222:223], off
	v_lshl_add_u64 v[222:223], s[42:43], 0, v[156:157]
	s_mov_b32 m0, s44
	s_nop 0
	global_load_lds_dwordx4 v[222:223], off
	v_lshl_add_u64 v[222:223], s[42:43], 0, v[160:161]
	s_add_i32 m0, s44, 0x2000
	s_nop 0
	global_load_lds_dwordx4 v[222:223], off
	v_lshl_add_u64 v[222:223], v[226:227], 0, s[28:29]
	s_mov_b32 m0, s51
	s_nop 0
	global_load_lds_dwordx4 v[222:223], off
	v_lshl_add_u64 v[222:223], v[228:229], 0, s[28:29]
	s_mov_b32 m0, s59
	s_nop 0
	global_load_lds_dwordx4 v[222:223], off
	s_waitcnt vmcnt(8)
	s_waitcnt lgkmcnt(0)
	s_barrier
	s_setprio 1
	s_waitcnt lgkmcnt(0)
	v_mfma_f32_16x16x32_bf16 v[62:65], v[130:133], v[186:189], v[62:65]
	v_mfma_f32_16x16x32_bf16 v[62:65], v[134:137], v[194:197], v[62:65]
	v_mfma_f32_16x16x32_bf16 v[58:61], v[138:141], v[186:189], v[58:61]
	v_mfma_f32_16x16x32_bf16 v[58:61], v[142:145], v[194:197], v[58:61]
	v_mfma_f32_16x16x32_bf16 v[46:49], v[130:133], v[198:201], v[46:49]
	v_mfma_f32_16x16x32_bf16 v[46:49], v[134:137], v[202:205], v[46:49]
	v_mfma_f32_16x16x32_bf16 v[42:45], v[138:141], v[198:201], v[42:45]
	v_mfma_f32_16x16x32_bf16 v[42:45], v[142:145], v[202:205], v[42:45]
	v_mfma_f32_16x16x32_bf16 v[30:33], v[130:133], v[206:209], v[30:33]
	v_mfma_f32_16x16x32_bf16 v[30:33], v[134:137], v[210:213], v[30:33]
	v_mfma_f32_16x16x32_bf16 v[26:29], v[138:141], v[206:209], v[26:29]
	v_mfma_f32_16x16x32_bf16 v[26:29], v[142:145], v[210:213], v[26:29]
	v_mfma_f32_16x16x32_bf16 v[14:17], v[130:133], v[214:217], v[14:17]
	v_mfma_f32_16x16x32_bf16 v[14:17], v[134:137], v[218:221], v[14:17]
	v_mfma_f32_16x16x32_bf16 v[10:13], v[138:141], v[214:217], v[10:13]
	v_mfma_f32_16x16x32_bf16 v[10:13], v[142:145], v[218:221], v[10:13]
	s_setprio 0
	s_setprio 1
	v_mfma_f32_16x16x32_bf16 v[54:57], v[146:149], v[186:189], v[54:57]
	v_mfma_f32_16x16x32_bf16 v[54:57], v[150:153], v[194:197], v[54:57]
	v_mfma_f32_16x16x32_bf16 v[50:53], v[174:177], v[186:189], v[50:53]
	v_mfma_f32_16x16x32_bf16 v[50:53], v[178:181], v[194:197], v[50:53]
	v_mfma_f32_16x16x32_bf16 v[38:41], v[146:149], v[198:201], v[38:41]
	v_mfma_f32_16x16x32_bf16 v[38:41], v[150:153], v[202:205], v[38:41]
	v_mfma_f32_16x16x32_bf16 v[34:37], v[174:177], v[198:201], v[34:37]
	v_mfma_f32_16x16x32_bf16 v[34:37], v[178:181], v[202:205], v[34:37]
	v_mfma_f32_16x16x32_bf16 v[22:25], v[146:149], v[206:209], v[22:25]
	v_mfma_f32_16x16x32_bf16 v[22:25], v[150:153], v[210:213], v[22:25]
	v_mfma_f32_16x16x32_bf16 v[18:21], v[174:177], v[206:209], v[18:21]
	v_mfma_f32_16x16x32_bf16 v[18:21], v[178:181], v[210:213], v[18:21]
	v_mfma_f32_16x16x32_bf16 v[6:9], v[146:149], v[214:217], v[6:9]
	v_mfma_f32_16x16x32_bf16 v[6:9], v[150:153], v[218:221], v[6:9]
	v_mfma_f32_16x16x32_bf16 v[2:5], v[174:177], v[214:217], v[2:5]
	v_mfma_f32_16x16x32_bf16 v[2:5], v[178:181], v[218:221], v[2:5]
	s_setprio 0
	s_barrier
	s_add_i32 s71, s71, 2
	s_add_u32 s40, s40, 0x100
	s_addc_u32 s41, s41, 0
	s_add_u32 s12, s12, 0x100
	s_addc_u32 s70, s70, 0
	s_cmpk_gt_u32 s71, 0xa9
	s_cbranch_scc0 .LBB0_2340
	s_and_b64 vcc, exec, s[36:37]
	s_cbranch_vccz .LBB0_2343
	s_barrier

.LBB0_2464:
	ds_read_b128 v[150:153], v167
	ds_read_b128 v[172:175], v167 offset:1024
	ds_read_b128 v[176:179], v167 offset:2048
	ds_read_b128 v[184:187], v167 offset:3072
	ds_read_b128 v[188:191], v168
	ds_read_b128 v[192:195], v168 offset:1024
	ds_read_b128 v[196:199], v168 offset:2048
	ds_read_b128 v[200:203], v168 offset:3072
	s_add_u32 s74, s6, 0xfff00080
	s_addc_u32 s75, s7, -1
	s_cmp_eq_u32 s87, 60
	s_cselect_b32 s77, s47, s75
	s_cselect_b32 s76, s83, s74
	s_cselect_b32 s75, s45, s86
	s_cselect_b32 s74, s84, s85
	v_lshl_add_u64 v[154:155], s[6:7], 0, v[142:143]
	s_add_i32 m0, s59, 0xc000
	ds_read_b128 v[204:207], v169
	ds_read_b128 v[208:211], v169 offset:1024
	ds_read_b128 v[212:215], v169 offset:2048
	ds_read_b128 v[216:219], v169 offset:3072
	ds_read_b128 v[220:223], v169 offset:4096
	ds_read_b128 v[224:227], v169 offset:5120
	ds_read_b128 v[228:231], v169 offset:6144
	ds_read_b128 v[232:235], v169 offset:7168
	global_load_lds_dwordx4 v[154:155], off
	v_lshl_add_u64 v[154:155], s[6:7], 0, v[144:145]
	s_add_i32 m0, s59, 0xe000
	s_nop 0
	global_load_lds_dwordx4 v[154:155], off
	s_waitcnt vmcnt(8)
	s_waitcnt lgkmcnt(0)
	s_barrier
	s_setprio 1
	s_waitcnt lgkmcnt(0)
	v_mfma_f32_16x16x32_bf16 v[126:129], v[150:153], v[204:207], v[126:129]
	v_mfma_f32_16x16x32_bf16 v[126:129], v[172:175], v[208:211], v[126:129]
	v_mfma_f32_16x16x32_bf16 v[122:125], v[176:179], v[204:207], v[122:125]
	v_mfma_f32_16x16x32_bf16 v[122:125], v[184:187], v[208:211], v[122:125]
	v_mfma_f32_16x16x32_bf16 v[110:113], v[150:153], v[212:215], v[110:113]
	v_mfma_f32_16x16x32_bf16 v[110:113], v[172:175], v[216:219], v[110:113]
	v_mfma_f32_16x16x32_bf16 v[106:109], v[176:179], v[212:215], v[106:109]
	v_mfma_f32_16x16x32_bf16 v[106:109], v[184:187], v[216:219], v[106:109]
	v_mfma_f32_16x16x32_bf16 v[94:97], v[150:153], v[220:223], v[94:97]
	v_mfma_f32_16x16x32_bf16 v[94:97], v[172:175], v[224:227], v[94:97]
	v_mfma_f32_16x16x32_bf16 v[90:93], v[176:179], v[220:223], v[90:93]
	v_mfma_f32_16x16x32_bf16 v[90:93], v[184:187], v[224:227], v[90:93]
	v_mfma_f32_16x16x32_bf16 v[78:81], v[150:153], v[228:231], v[78:81]
	v_mfma_f32_16x16x32_bf16 v[78:81], v[172:175], v[232:235], v[78:81]
	v_mfma_f32_16x16x32_bf16 v[74:77], v[176:179], v[228:231], v[74:77]
	v_mfma_f32_16x16x32_bf16 v[74:77], v[184:187], v[232:235], v[74:77]
	s_setprio 0
	s_setprio 1
	v_mfma_f32_16x16x32_bf16 v[118:121], v[188:191], v[204:207], v[118:121]
	v_mfma_f32_16x16x32_bf16 v[118:121], v[192:195], v[208:211], v[118:121]
	v_mfma_f32_16x16x32_bf16 v[114:117], v[196:199], v[204:207], v[114:117]
	v_mfma_f32_16x16x32_bf16 v[114:117], v[200:203], v[208:211], v[114:117]
	v_mfma_f32_16x16x32_bf16 v[102:105], v[188:191], v[212:215], v[102:105]
	v_mfma_f32_16x16x32_bf16 v[102:105], v[192:195], v[216:219], v[102:105]
	v_mfma_f32_16x16x32_bf16 v[98:101], v[196:199], v[212:215], v[98:101]
	v_mfma_f32_16x16x32_bf16 v[98:101], v[200:203], v[216:219], v[98:101]
	v_mfma_f32_16x16x32_bf16 v[86:89], v[188:191], v[220:223], v[86:89]
	v_mfma_f32_16x16x32_bf16 v[86:89], v[192:195], v[224:227], v[86:89]
	v_mfma_f32_16x16x32_bf16 v[82:85], v[196:199], v[220:223], v[82:85]
	v_mfma_f32_16x16x32_bf16 v[82:85], v[200:203], v[224:227], v[82:85]
	v_mfma_f32_16x16x32_bf16 v[70:73], v[188:191], v[228:231], v[70:73]
	v_mfma_f32_16x16x32_bf16 v[70:73], v[192:195], v[232:235], v[70:73]
	v_mfma_f32_16x16x32_bf16 v[66:69], v[196:199], v[228:231], v[66:69]
	v_mfma_f32_16x16x32_bf16 v[66:69], v[200:203], v[232:235], v[66:69]
	s_setprio 0
	s_barrier
	s_add_i32 s88, s70, s27
	v_lshl_add_u64 v[154:155], s[74:75], 0, v[132:133]
	s_mov_b32 m0, s88
	ds_read_b128 v[204:207], v169 offset:16384
	ds_read_b128 v[208:211], v169 offset:17408
	ds_read_b128 v[212:215], v169 offset:18432
	ds_read_b128 v[216:219], v169 offset:19456
	ds_read_b128 v[220:223], v169 offset:20480
	ds_read_b128 v[224:227], v169 offset:21504
	ds_read_b128 v[228:231], v169 offset:22528
	ds_read_b128 v[232:235], v169 offset:23552
	global_load_lds_dwordx4 v[154:155], off
	s_add_i32 m0, s88, 0x2000
	s_add_u32 s88, s74, 0x100000
	v_lshl_add_u64 v[180:181], s[74:75], 0, v[136:137]
	s_addc_u32 s89, s75, 0
	s_add_i32 s90, s71, s27
	global_load_lds_dwordx4 v[180:181], off
	v_lshl_add_u64 v[236:237], s[88:89], 0, v[132:133]
	s_mov_b32 m0, s90
	v_lshl_add_u64 v[238:239], s[76:77], 0, v[134:135]
	global_load_lds_dwordx4 v[236:237], off
	v_lshl_add_u64 v[236:237], s[88:89], 0, v[136:137]
	s_add_i32 m0, s90, 0x2000
	s_nop 0
	global_load_lds_dwordx4 v[236:237], off
	v_lshl_add_u64 v[236:237], s[76:77], 0, v[130:131]
	s_mov_b32 m0, s59
	s_nop 0
	global_load_lds_dwordx4 v[236:237], off
	s_mov_b32 m0, s62
	s_nop 0
	global_load_lds_dwordx4 v[238:239], off
	s_waitcnt vmcnt(8)
	s_waitcnt lgkmcnt(0)
	s_barrier
	s_setprio 1
	s_waitcnt lgkmcnt(0)
	v_mfma_f32_16x16x32_bf16 v[62:65], v[150:153], v[204:207], v[62:65]
	v_mfma_f32_16x16x32_bf16 v[62:65], v[172:175], v[208:211], v[62:65]
	v_mfma_f32_16x16x32_bf16 v[58:61], v[176:179], v[204:207], v[58:61]
	v_mfma_f32_16x16x32_bf16 v[58:61], v[184:187], v[208:211], v[58:61]
	v_mfma_f32_16x16x32_bf16 v[50:53], v[150:153], v[212:215], v[50:53]
	v_mfma_f32_16x16x32_bf16 v[50:53], v[172:175], v[216:219], v[50:53]
	v_mfma_f32_16x16x32_bf16 v[42:45], v[176:179], v[212:215], v[42:45]
	v_mfma_f32_16x16x32_bf16 v[42:45], v[184:187], v[216:219], v[42:45]
	v_mfma_f32_16x16x32_bf16 v[34:37], v[150:153], v[220:223], v[34:37]
	v_mfma_f32_16x16x32_bf16 v[34:37], v[172:175], v[224:227], v[34:37]
	v_mfma_f32_16x16x32_bf16 v[26:29], v[176:179], v[220:223], v[26:29]
	v_mfma_f32_16x16x32_bf16 v[26:29], v[184:187], v[224:227], v[26:29]
	v_mfma_f32_16x16x32_bf16 v[18:21], v[150:153], v[228:231], v[18:21]
	v_mfma_f32_16x16x32_bf16 v[18:21], v[172:175], v[232:235], v[18:21]
	v_mfma_f32_16x16x32_bf16 v[10:13], v[176:179], v[228:231], v[10:13]
	v_mfma_f32_16x16x32_bf16 v[10:13], v[184:187], v[232:235], v[10:13]
	s_setprio 0
	s_setprio 1
	v_mfma_f32_16x16x32_bf16 v[54:57], v[188:191], v[204:207], v[54:57]
	v_mfma_f32_16x16x32_bf16 v[54:57], v[192:195], v[208:211], v[54:57]
	v_mfma_f32_16x16x32_bf16 v[46:49], v[196:199], v[204:207], v[46:49]
	v_mfma_f32_16x16x32_bf16 v[46:49], v[200:203], v[208:211], v[46:49]
	v_mfma_f32_16x16x32_bf16 v[38:41], v[188:191], v[212:215], v[38:41]
	v_mfma_f32_16x16x32_bf16 v[38:41], v[192:195], v[216:219], v[38:41]
	v_mfma_f32_16x16x32_bf16 v[30:33], v[196:199], v[212:215], v[30:33]
	v_mfma_f32_16x16x32_bf16 v[30:33], v[200:203], v[216:219], v[30:33]
	v_mfma_f32_16x16x32_bf16 v[22:25], v[188:191], v[220:223], v[22:25]
	v_mfma_f32_16x16x32_bf16 v[22:25], v[192:195], v[224:227], v[22:25]
	v_mfma_f32_16x16x32_bf16 v[14:17], v[196:199], v[220:223], v[14:17]
	v_mfma_f32_16x16x32_bf16 v[14:17], v[200:203], v[224:227], v[14:17]
	v_mfma_f32_16x16x32_bf16 v[6:9], v[188:191], v[228:231], v[6:9]
	v_mfma_f32_16x16x32_bf16 v[6:9], v[192:195], v[232:235], v[6:9]
	v_mfma_f32_16x16x32_bf16 v[2:5], v[196:199], v[228:231], v[2:5]
	v_mfma_f32_16x16x32_bf16 v[2:5], v[200:203], v[232:235], v[2:5]
	s_setprio 0
	s_barrier
	s_add_i32 s88, 0, 0x18000
	v_add_u32_e32 v140, s88, v163
	s_add_i32 s89, 0, 0x1c000
	ds_read_b128 v[150:153], v140
	ds_read_b128 v[172:175], v140 offset:1024
	ds_read_b128 v[176:179], v140 offset:2048
	ds_read_b128 v[184:187], v140 offset:3072
	v_add_u32_e32 v140, s89, v163
	ds_read_b128 v[188:191], v140
	ds_read_b128 v[192:195], v140 offset:1024
	ds_read_b128 v[196:199], v140 offset:2048
	ds_read_b128 v[200:203], v140 offset:3072
	s_add_u32 s76, s76, 0x100000
	s_addc_u32 s77, s77, 0
	s_mov_b32 m0, s63
	v_lshl_add_u64 v[240:241], s[76:77], 0, v[130:131]
	ds_read_b128 v[204:207], v169 offset:32768
	ds_read_b128 v[208:211], v169 offset:33792
	ds_read_b128 v[212:215], v169 offset:34816
	ds_read_b128 v[216:219], v169 offset:35840
	ds_read_b128 v[220:223], v169 offset:36864
	ds_read_b128 v[224:227], v169 offset:37888
	ds_read_b128 v[228:231], v169 offset:38912
	ds_read_b128 v[232:235], v169 offset:39936
	global_load_lds_dwordx4 v[240:241], off
	v_lshl_add_u64 v[240:241], s[76:77], 0, v[134:135]
	s_mov_b32 m0, s65
	s_nop 0
	global_load_lds_dwordx4 v[240:241], off
	s_waitcnt vmcnt(8)
	s_waitcnt lgkmcnt(0)
	s_barrier
	s_setprio 1
	s_waitcnt lgkmcnt(0)
	v_mfma_f32_16x16x32_bf16 v[126:129], v[150:153], v[204:207], v[126:129]
	v_mfma_f32_16x16x32_bf16 v[126:129], v[172:175], v[208:211], v[126:129]
	v_mfma_f32_16x16x32_bf16 v[122:125], v[176:179], v[204:207], v[122:125]
	v_mfma_f32_16x16x32_bf16 v[122:125], v[184:187], v[208:211], v[122:125]
	v_mfma_f32_16x16x32_bf16 v[110:113], v[150:153], v[212:215], v[110:113]
	v_mfma_f32_16x16x32_bf16 v[110:113], v[172:175], v[216:219], v[110:113]
	v_mfma_f32_16x16x32_bf16 v[106:109], v[176:179], v[212:215], v[106:109]
	v_mfma_f32_16x16x32_bf16 v[106:109], v[184:187], v[216:219], v[106:109]
	v_mfma_f32_16x16x32_bf16 v[94:97], v[150:153], v[220:223], v[94:97]
	v_mfma_f32_16x16x32_bf16 v[94:97], v[172:175], v[224:227], v[94:97]
	v_mfma_f32_16x16x32_bf16 v[90:93], v[176:179], v[220:223], v[90:93]
	v_mfma_f32_16x16x32_bf16 v[90:93], v[184:187], v[224:227], v[90:93]
	v_mfma_f32_16x16x32_bf16 v[78:81], v[150:153], v[228:231], v[78:81]
	v_mfma_f32_16x16x32_bf16 v[78:81], v[172:175], v[232:235], v[78:81]
	v_mfma_f32_16x16x32_bf16 v[74:77], v[176:179], v[228:231], v[74:77]
	v_mfma_f32_16x16x32_bf16 v[74:77], v[184:187], v[232:235], v[74:77]
	s_setprio 0
	s_setprio 1
	v_mfma_f32_16x16x32_bf16 v[118:121], v[188:191], v[204:207], v[118:121]
	v_mfma_f32_16x16x32_bf16 v[118:121], v[192:195], v[208:211], v[118:121]
	v_mfma_f32_16x16x32_bf16 v[114:117], v[196:199], v[204:207], v[114:117]
	v_mfma_f32_16x16x32_bf16 v[114:117], v[200:203], v[208:211], v[114:117]
	v_mfma_f32_16x16x32_bf16 v[102:105], v[188:191], v[212:215], v[102:105]
	v_mfma_f32_16x16x32_bf16 v[102:105], v[192:195], v[216:219], v[102:105]
	v_mfma_f32_16x16x32_bf16 v[98:101], v[196:199], v[212:215], v[98:101]
	v_mfma_f32_16x16x32_bf16 v[98:101], v[200:203], v[216:219], v[98:101]
	v_mfma_f32_16x16x32_bf16 v[86:89], v[188:191], v[220:223], v[86:89]
	v_mfma_f32_16x16x32_bf16 v[86:89], v[192:195], v[224:227], v[86:89]
	v_mfma_f32_16x16x32_bf16 v[82:85], v[196:199], v[220:223], v[82:85]
	v_mfma_f32_16x16x32_bf16 v[82:85], v[200:203], v[224:227], v[82:85]
	v_mfma_f32_16x16x32_bf16 v[70:73], v[188:191], v[228:231], v[70:73]
	v_mfma_f32_16x16x32_bf16 v[70:73], v[192:195], v[232:235], v[70:73]
	v_mfma_f32_16x16x32_bf16 v[66:69], v[196:199], v[228:231], v[66:69]
	v_mfma_f32_16x16x32_bf16 v[66:69], v[200:203], v[232:235], v[66:69]
	s_setprio 0
	s_barrier
	s_add_i32 s76, s88, s27
	v_lshl_add_u64 v[154:155], v[154:155], 0, s[36:37]
	s_mov_b32 m0, s76
	ds_read_b128 v[204:207], v169 offset:49152
	ds_read_b128 v[208:211], v169 offset:50176
	ds_read_b128 v[212:215], v169 offset:51200
	ds_read_b128 v[216:219], v169 offset:52224
	ds_read_b128 v[220:223], v169 offset:53248
	ds_read_b128 v[224:227], v169 offset:54272
	ds_read_b128 v[228:231], v169 offset:55296
	ds_read_b128 v[232:235], v169 offset:56320
	global_load_lds_dwordx4 v[154:155], off
	s_add_i32 m0, s76, 0x2000
	s_add_u32 s74, s74, 0x100080
	v_lshl_add_u64 v[154:155], v[180:181], 0, s[36:37]
	s_addc_u32 s75, s75, 0
	s_add_i32 s76, s89, s27
	global_load_lds_dwordx4 v[154:155], off
	v_lshl_add_u64 v[154:155], s[74:75], 0, v[132:133]
	s_mov_b32 m0, s76
	s_nop 0
	global_load_lds_dwordx4 v[154:155], off
	v_lshl_add_u64 v[154:155], s[74:75], 0, v[136:137]
	s_add_i32 m0, s76, 0x2000
	s_nop 0
	global_load_lds_dwordx4 v[154:155], off
	v_lshl_add_u64 v[154:155], v[236:237], 0, s[36:37]
	s_mov_b32 m0, s67
	s_nop 0
	global_load_lds_dwordx4 v[154:155], off
	v_lshl_add_u64 v[154:155], v[238:239], 0, s[36:37]
	s_mov_b32 m0, s68
	s_nop 0
	global_load_lds_dwordx4 v[154:155], off
	s_waitcnt vmcnt(8)
	s_waitcnt lgkmcnt(0)
	s_barrier
	s_setprio 1
	s_waitcnt lgkmcnt(0)
	v_mfma_f32_16x16x32_bf16 v[62:65], v[150:153], v[204:207], v[62:65]
	v_mfma_f32_16x16x32_bf16 v[62:65], v[172:175], v[208:211], v[62:65]
	v_mfma_f32_16x16x32_bf16 v[58:61], v[176:179], v[204:207], v[58:61]
	v_mfma_f32_16x16x32_bf16 v[58:61], v[184:187], v[208:211], v[58:61]
	v_mfma_f32_16x16x32_bf16 v[50:53], v[150:153], v[212:215], v[50:53]
	v_mfma_f32_16x16x32_bf16 v[50:53], v[172:175], v[216:219], v[50:53]
	v_mfma_f32_16x16x32_bf16 v[42:45], v[176:179], v[212:215], v[42:45]
	v_mfma_f32_16x16x32_bf16 v[42:45], v[184:187], v[216:219], v[42:45]
	v_mfma_f32_16x16x32_bf16 v[34:37], v[150:153], v[220:223], v[34:37]
	v_mfma_f32_16x16x32_bf16 v[34:37], v[172:175], v[224:227], v[34:37]
	v_mfma_f32_16x16x32_bf16 v[26:29], v[176:179], v[220:223], v[26:29]
	v_mfma_f32_16x16x32_bf16 v[26:29], v[184:187], v[224:227], v[26:29]
	v_mfma_f32_16x16x32_bf16 v[18:21], v[150:153], v[228:231], v[18:21]
	v_mfma_f32_16x16x32_bf16 v[18:21], v[172:175], v[232:235], v[18:21]
	v_mfma_f32_16x16x32_bf16 v[10:13], v[176:179], v[228:231], v[10:13]
	v_mfma_f32_16x16x32_bf16 v[10:13], v[184:187], v[232:235], v[10:13]
	s_setprio 0
	s_setprio 1
	v_mfma_f32_16x16x32_bf16 v[54:57], v[188:191], v[204:207], v[54:57]
	v_mfma_f32_16x16x32_bf16 v[54:57], v[192:195], v[208:211], v[54:57]
	v_mfma_f32_16x16x32_bf16 v[46:49], v[196:199], v[204:207], v[46:49]
	v_mfma_f32_16x16x32_bf16 v[46:49], v[200:203], v[208:211], v[46:49]
	v_mfma_f32_16x16x32_bf16 v[38:41], v[188:191], v[212:215], v[38:41]
	v_mfma_f32_16x16x32_bf16 v[38:41], v[192:195], v[216:219], v[38:41]
	v_mfma_f32_16x16x32_bf16 v[30:33], v[196:199], v[212:215], v[30:33]
	v_mfma_f32_16x16x32_bf16 v[30:33], v[200:203], v[216:219], v[30:33]
	v_mfma_f32_16x16x32_bf16 v[22:25], v[188:191], v[220:223], v[22:25]
	v_mfma_f32_16x16x32_bf16 v[22:25], v[192:195], v[224:227], v[22:25]
	v_mfma_f32_16x16x32_bf16 v[14:17], v[196:199], v[220:223], v[14:17]
	v_mfma_f32_16x16x32_bf16 v[14:17], v[200:203], v[224:227], v[14:17]
	v_mfma_f32_16x16x32_bf16 v[6:9], v[188:191], v[228:231], v[6:9]
	v_mfma_f32_16x16x32_bf16 v[6:9], v[192:195], v[232:235], v[6:9]
	v_mfma_f32_16x16x32_bf16 v[2:5], v[196:199], v[228:231], v[2:5]
	v_mfma_f32_16x16x32_bf16 v[2:5], v[200:203], v[232:235], v[2:5]
	s_setprio 0
	s_barrier
	s_add_i32 s87, s87, 2
	s_add_u32 s6, s6, 0x100
	s_addc_u32 s7, s7, 0
	s_add_u32 s85, s85, 0x100
	s_addc_u32 s86, s86, 0
	s_cmp_gt_u32 s87, 61
	s_cbranch_scc0 .LBB0_2464
	s_and_b64 vcc, exec, s[38:39]
	s_cbranch_vccz .LBB0_2467
	s_barrier

.LBB0_2494:
	ds_read_b128 v[160:163], v155
	ds_read_b128 v[164:167], v155 offset:1024
	ds_read_b128 v[168:171], v155 offset:2048
	ds_read_b128 v[172:175], v155 offset:3072
	ds_read_b128 v[176:179], v156
	ds_read_b128 v[184:187], v156 offset:1024
	ds_read_b128 v[188:191], v156 offset:2048
	ds_read_b128 v[192:195], v156 offset:3072
	s_add_u32 s48, s6, 0xfff00080
	s_addc_u32 s49, s7, -1
	s_cmp_eq_u32 s89, 60
	s_cselect_b32 s51, s43, s49
	s_cselect_b32 s50, s85, s48
	s_cselect_b32 s49, s41, s88
	s_cselect_b32 s48, s86, s87
	v_lshl_add_u64 v[148:149], s[6:7], 0, v[140:141]
	s_add_i32 m0, s63, 0xc000
	ds_read_b128 v[196:199], v157
	ds_read_b128 v[200:203], v157 offset:1024
	ds_read_b128 v[204:207], v157 offset:2048
	ds_read_b128 v[208:211], v157 offset:3072
	ds_read_b128 v[212:215], v157 offset:4096
	ds_read_b128 v[216:219], v157 offset:5120
	ds_read_b128 v[220:223], v157 offset:6144
	ds_read_b128 v[224:227], v157 offset:7168
	global_load_lds_dwordx4 v[148:149], off
	v_lshl_add_u64 v[148:149], s[6:7], 0, v[142:143]
	s_add_i32 m0, s63, 0xe000
	s_nop 0
	global_load_lds_dwordx4 v[148:149], off
	s_waitcnt vmcnt(8)
	s_waitcnt lgkmcnt(0)
	s_barrier
	s_setprio 1
	s_waitcnt lgkmcnt(0)
	v_mfma_f32_16x16x32_bf16 v[126:129], v[160:163], v[196:199], v[126:129]
	v_mfma_f32_16x16x32_bf16 v[126:129], v[164:167], v[200:203], v[126:129]
	v_mfma_f32_16x16x32_bf16 v[122:125], v[168:171], v[196:199], v[122:125]
	v_mfma_f32_16x16x32_bf16 v[122:125], v[172:175], v[200:203], v[122:125]
	v_mfma_f32_16x16x32_bf16 v[110:113], v[160:163], v[204:207], v[110:113]
	v_mfma_f32_16x16x32_bf16 v[110:113], v[164:167], v[208:211], v[110:113]
	v_mfma_f32_16x16x32_bf16 v[106:109], v[168:171], v[204:207], v[106:109]
	v_mfma_f32_16x16x32_bf16 v[106:109], v[172:175], v[208:211], v[106:109]
	v_mfma_f32_16x16x32_bf16 v[94:97], v[160:163], v[212:215], v[94:97]
	v_mfma_f32_16x16x32_bf16 v[94:97], v[164:167], v[216:219], v[94:97]
	v_mfma_f32_16x16x32_bf16 v[90:93], v[168:171], v[212:215], v[90:93]
	v_mfma_f32_16x16x32_bf16 v[90:93], v[172:175], v[216:219], v[90:93]
	v_mfma_f32_16x16x32_bf16 v[78:81], v[160:163], v[220:223], v[78:81]
	v_mfma_f32_16x16x32_bf16 v[78:81], v[164:167], v[224:227], v[78:81]
	v_mfma_f32_16x16x32_bf16 v[74:77], v[168:171], v[220:223], v[74:77]
	v_mfma_f32_16x16x32_bf16 v[74:77], v[172:175], v[224:227], v[74:77]
	s_setprio 0
	s_setprio 1
	v_mfma_f32_16x16x32_bf16 v[118:121], v[176:179], v[196:199], v[118:121]
	v_mfma_f32_16x16x32_bf16 v[118:121], v[184:187], v[200:203], v[118:121]
	v_mfma_f32_16x16x32_bf16 v[114:117], v[188:191], v[196:199], v[114:117]
	v_mfma_f32_16x16x32_bf16 v[114:117], v[192:195], v[200:203], v[114:117]
	v_mfma_f32_16x16x32_bf16 v[102:105], v[176:179], v[204:207], v[102:105]
	v_mfma_f32_16x16x32_bf16 v[102:105], v[184:187], v[208:211], v[102:105]
	v_mfma_f32_16x16x32_bf16 v[98:101], v[188:191], v[204:207], v[98:101]
	v_mfma_f32_16x16x32_bf16 v[98:101], v[192:195], v[208:211], v[98:101]
	v_mfma_f32_16x16x32_bf16 v[86:89], v[176:179], v[212:215], v[86:89]
	v_mfma_f32_16x16x32_bf16 v[86:89], v[184:187], v[216:219], v[86:89]
	v_mfma_f32_16x16x32_bf16 v[82:85], v[188:191], v[212:215], v[82:85]
	v_mfma_f32_16x16x32_bf16 v[82:85], v[192:195], v[216:219], v[82:85]
	v_mfma_f32_16x16x32_bf16 v[70:73], v[176:179], v[220:223], v[70:73]
	v_mfma_f32_16x16x32_bf16 v[70:73], v[184:187], v[224:227], v[70:73]
	v_mfma_f32_16x16x32_bf16 v[66:69], v[188:191], v[220:223], v[66:69]
	v_mfma_f32_16x16x32_bf16 v[66:69], v[192:195], v[224:227], v[66:69]
	s_setprio 0
	s_barrier
	s_add_i32 s90, s73, s27
	v_lshl_add_u64 v[148:149], s[48:49], 0, v[132:133]
	s_mov_b32 m0, s90
	ds_read_b128 v[196:199], v157 offset:16384
	ds_read_b128 v[200:203], v157 offset:17408
	ds_read_b128 v[204:207], v157 offset:18432
	ds_read_b128 v[208:211], v157 offset:19456
	ds_read_b128 v[212:215], v157 offset:20480
	ds_read_b128 v[216:219], v157 offset:21504
	ds_read_b128 v[220:223], v157 offset:22528
	ds_read_b128 v[224:227], v157 offset:23552
	global_load_lds_dwordx4 v[148:149], off
	s_add_i32 m0, s90, 0x2000
	s_add_u32 s90, s48, 0x100000
	v_lshl_add_u64 v[180:181], s[48:49], 0, v[136:137]
	s_addc_u32 s91, s49, 0
	s_add_i32 s92, s74, s27
	global_load_lds_dwordx4 v[180:181], off
	v_lshl_add_u64 v[228:229], s[90:91], 0, v[132:133]
	s_mov_b32 m0, s92
	v_lshl_add_u64 v[230:231], s[50:51], 0, v[134:135]
	global_load_lds_dwordx4 v[228:229], off
	v_lshl_add_u64 v[228:229], s[90:91], 0, v[136:137]
	s_add_i32 m0, s92, 0x2000
	s_nop 0
	global_load_lds_dwordx4 v[228:229], off
	v_lshl_add_u64 v[228:229], s[50:51], 0, v[130:131]
	s_mov_b32 m0, s63
	s_nop 0
	global_load_lds_dwordx4 v[228:229], off
	s_mov_b32 m0, s65
	s_nop 0
	global_load_lds_dwordx4 v[230:231], off
	s_waitcnt vmcnt(8)
	s_waitcnt lgkmcnt(0)
	s_barrier
	s_setprio 1
	s_waitcnt lgkmcnt(0)
	v_mfma_f32_16x16x32_bf16 v[62:65], v[160:163], v[196:199], v[62:65]
	v_mfma_f32_16x16x32_bf16 v[62:65], v[164:167], v[200:203], v[62:65]
	v_mfma_f32_16x16x32_bf16 v[58:61], v[168:171], v[196:199], v[58:61]
	v_mfma_f32_16x16x32_bf16 v[58:61], v[172:175], v[200:203], v[58:61]
	v_mfma_f32_16x16x32_bf16 v[50:53], v[160:163], v[204:207], v[50:53]
	v_mfma_f32_16x16x32_bf16 v[50:53], v[164:167], v[208:211], v[50:53]
	v_mfma_f32_16x16x32_bf16 v[42:45], v[168:171], v[204:207], v[42:45]
	v_mfma_f32_16x16x32_bf16 v[42:45], v[172:175], v[208:211], v[42:45]
	v_mfma_f32_16x16x32_bf16 v[34:37], v[160:163], v[212:215], v[34:37]
	v_mfma_f32_16x16x32_bf16 v[34:37], v[164:167], v[216:219], v[34:37]
	v_mfma_f32_16x16x32_bf16 v[26:29], v[168:171], v[212:215], v[26:29]
	v_mfma_f32_16x16x32_bf16 v[26:29], v[172:175], v[216:219], v[26:29]
	v_mfma_f32_16x16x32_bf16 v[18:21], v[160:163], v[220:223], v[18:21]
	v_mfma_f32_16x16x32_bf16 v[18:21], v[164:167], v[224:227], v[18:21]
	v_mfma_f32_16x16x32_bf16 v[10:13], v[168:171], v[220:223], v[10:13]
	v_mfma_f32_16x16x32_bf16 v[10:13], v[172:175], v[224:227], v[10:13]
	s_setprio 0
	s_setprio 1
	v_mfma_f32_16x16x32_bf16 v[54:57], v[176:179], v[196:199], v[54:57]
	v_mfma_f32_16x16x32_bf16 v[54:57], v[184:187], v[200:203], v[54:57]
	v_mfma_f32_16x16x32_bf16 v[46:49], v[188:191], v[196:199], v[46:49]
	v_mfma_f32_16x16x32_bf16 v[46:49], v[192:195], v[200:203], v[46:49]
	v_mfma_f32_16x16x32_bf16 v[38:41], v[176:179], v[204:207], v[38:41]
	v_mfma_f32_16x16x32_bf16 v[38:41], v[184:187], v[208:211], v[38:41]
	v_mfma_f32_16x16x32_bf16 v[30:33], v[188:191], v[204:207], v[30:33]
	v_mfma_f32_16x16x32_bf16 v[30:33], v[192:195], v[208:211], v[30:33]
	v_mfma_f32_16x16x32_bf16 v[22:25], v[176:179], v[212:215], v[22:25]
	v_mfma_f32_16x16x32_bf16 v[22:25], v[184:187], v[216:219], v[22:25]
	v_mfma_f32_16x16x32_bf16 v[14:17], v[188:191], v[212:215], v[14:17]
	v_mfma_f32_16x16x32_bf16 v[14:17], v[192:195], v[216:219], v[14:17]
	v_mfma_f32_16x16x32_bf16 v[6:9], v[176:179], v[220:223], v[6:9]
	v_mfma_f32_16x16x32_bf16 v[6:9], v[184:187], v[224:227], v[6:9]
	v_mfma_f32_16x16x32_bf16 v[2:5], v[188:191], v[220:223], v[2:5]
	v_mfma_f32_16x16x32_bf16 v[2:5], v[192:195], v[224:227], v[2:5]
	s_setprio 0
	s_barrier
	s_add_i32 s90, 0, 0x18000
	v_add_u32_e32 v138, s90, v151
	s_add_i32 s91, 0, 0x1c000
	ds_read_b128 v[160:163], v138
	ds_read_b128 v[164:167], v138 offset:1024
	ds_read_b128 v[168:171], v138 offset:2048
	ds_read_b128 v[172:175], v138 offset:3072
	v_add_u32_e32 v138, s91, v151
	ds_read_b128 v[176:179], v138
	ds_read_b128 v[184:187], v138 offset:1024
	ds_read_b128 v[188:191], v138 offset:2048
	ds_read_b128 v[192:195], v138 offset:3072
	s_add_u32 s50, s50, 0x100000
	s_addc_u32 s51, s51, 0
	s_mov_b32 m0, s66
	v_lshl_add_u64 v[232:233], s[50:51], 0, v[130:131]
	ds_read_b128 v[196:199], v157 offset:32768
	ds_read_b128 v[200:203], v157 offset:33792
	ds_read_b128 v[204:207], v157 offset:34816
	ds_read_b128 v[208:211], v157 offset:35840
	ds_read_b128 v[212:215], v157 offset:36864
	ds_read_b128 v[216:219], v157 offset:37888
	ds_read_b128 v[220:223], v157 offset:38912
	ds_read_b128 v[224:227], v157 offset:39936
	global_load_lds_dwordx4 v[232:233], off
	v_lshl_add_u64 v[232:233], s[50:51], 0, v[134:135]
	s_mov_b32 m0, s67
	s_nop 0
	global_load_lds_dwordx4 v[232:233], off
	s_waitcnt vmcnt(8)
	s_waitcnt lgkmcnt(0)
	s_barrier
	s_setprio 1
	s_waitcnt lgkmcnt(0)
	v_mfma_f32_16x16x32_bf16 v[126:129], v[160:163], v[196:199], v[126:129]
	v_mfma_f32_16x16x32_bf16 v[126:129], v[164:167], v[200:203], v[126:129]
	v_mfma_f32_16x16x32_bf16 v[122:125], v[168:171], v[196:199], v[122:125]
	v_mfma_f32_16x16x32_bf16 v[122:125], v[172:175], v[200:203], v[122:125]
	v_mfma_f32_16x16x32_bf16 v[110:113], v[160:163], v[204:207], v[110:113]
	v_mfma_f32_16x16x32_bf16 v[110:113], v[164:167], v[208:211], v[110:113]
	v_mfma_f32_16x16x32_bf16 v[106:109], v[168:171], v[204:207], v[106:109]
	v_mfma_f32_16x16x32_bf16 v[106:109], v[172:175], v[208:211], v[106:109]
	v_mfma_f32_16x16x32_bf16 v[94:97], v[160:163], v[212:215], v[94:97]
	v_mfma_f32_16x16x32_bf16 v[94:97], v[164:167], v[216:219], v[94:97]
	v_mfma_f32_16x16x32_bf16 v[90:93], v[168:171], v[212:215], v[90:93]
	v_mfma_f32_16x16x32_bf16 v[90:93], v[172:175], v[216:219], v[90:93]
	v_mfma_f32_16x16x32_bf16 v[78:81], v[160:163], v[220:223], v[78:81]
	v_mfma_f32_16x16x32_bf16 v[78:81], v[164:167], v[224:227], v[78:81]
	v_mfma_f32_16x16x32_bf16 v[74:77], v[168:171], v[220:223], v[74:77]
	v_mfma_f32_16x16x32_bf16 v[74:77], v[172:175], v[224:227], v[74:77]
	s_setprio 0
	s_setprio 1
	v_mfma_f32_16x16x32_bf16 v[118:121], v[176:179], v[196:199], v[118:121]
	v_mfma_f32_16x16x32_bf16 v[118:121], v[184:187], v[200:203], v[118:121]
	v_mfma_f32_16x16x32_bf16 v[114:117], v[188:191], v[196:199], v[114:117]
	v_mfma_f32_16x16x32_bf16 v[114:117], v[192:195], v[200:203], v[114:117]
	v_mfma_f32_16x16x32_bf16 v[102:105], v[176:179], v[204:207], v[102:105]
	v_mfma_f32_16x16x32_bf16 v[102:105], v[184:187], v[208:211], v[102:105]
	v_mfma_f32_16x16x32_bf16 v[98:101], v[188:191], v[204:207], v[98:101]
	v_mfma_f32_16x16x32_bf16 v[98:101], v[192:195], v[208:211], v[98:101]
	v_mfma_f32_16x16x32_bf16 v[86:89], v[176:179], v[212:215], v[86:89]
	v_mfma_f32_16x16x32_bf16 v[86:89], v[184:187], v[216:219], v[86:89]
	v_mfma_f32_16x16x32_bf16 v[82:85], v[188:191], v[212:215], v[82:85]
	v_mfma_f32_16x16x32_bf16 v[82:85], v[192:195], v[216:219], v[82:85]
	v_mfma_f32_16x16x32_bf16 v[70:73], v[176:179], v[220:223], v[70:73]
	v_mfma_f32_16x16x32_bf16 v[70:73], v[184:187], v[224:227], v[70:73]
	v_mfma_f32_16x16x32_bf16 v[66:69], v[188:191], v[220:223], v[66:69]
	v_mfma_f32_16x16x32_bf16 v[66:69], v[192:195], v[224:227], v[66:69]
	s_setprio 0
	s_barrier
	s_add_i32 s50, s90, s27
	v_lshl_add_u64 v[148:149], v[148:149], 0, s[36:37]
	s_mov_b32 m0, s50
	ds_read_b128 v[196:199], v157 offset:49152
	ds_read_b128 v[200:203], v157 offset:50176
	ds_read_b128 v[204:207], v157 offset:51200
	ds_read_b128 v[208:211], v157 offset:52224
	ds_read_b128 v[212:215], v157 offset:53248
	ds_read_b128 v[216:219], v157 offset:54272
	ds_read_b128 v[220:223], v157 offset:55296
	ds_read_b128 v[224:227], v157 offset:56320
	global_load_lds_dwordx4 v[148:149], off
	s_add_i32 m0, s50, 0x2000
	s_add_u32 s48, s48, 0x100080
	v_lshl_add_u64 v[148:149], v[180:181], 0, s[36:37]
	s_addc_u32 s49, s49, 0
	s_add_i32 s50, s91, s27
	global_load_lds_dwordx4 v[148:149], off
	v_lshl_add_u64 v[148:149], s[48:49], 0, v[132:133]
	s_mov_b32 m0, s50
	s_nop 0
	global_load_lds_dwordx4 v[148:149], off
	v_lshl_add_u64 v[148:149], s[48:49], 0, v[136:137]
	s_add_i32 m0, s50, 0x2000
	s_nop 0
	global_load_lds_dwordx4 v[148:149], off
	v_lshl_add_u64 v[148:149], v[228:229], 0, s[36:37]
	s_mov_b32 m0, s69
	s_nop 0
	global_load_lds_dwordx4 v[148:149], off
	v_lshl_add_u64 v[148:149], v[230:231], 0, s[36:37]
	s_mov_b32 m0, s70
	s_nop 0
	global_load_lds_dwordx4 v[148:149], off
	s_waitcnt vmcnt(8)
	s_waitcnt lgkmcnt(0)
	s_barrier
	s_setprio 1
	s_waitcnt lgkmcnt(0)
	v_mfma_f32_16x16x32_bf16 v[62:65], v[160:163], v[196:199], v[62:65]
	v_mfma_f32_16x16x32_bf16 v[62:65], v[164:167], v[200:203], v[62:65]
	v_mfma_f32_16x16x32_bf16 v[58:61], v[168:171], v[196:199], v[58:61]
	v_mfma_f32_16x16x32_bf16 v[58:61], v[172:175], v[200:203], v[58:61]
	v_mfma_f32_16x16x32_bf16 v[50:53], v[160:163], v[204:207], v[50:53]
	v_mfma_f32_16x16x32_bf16 v[50:53], v[164:167], v[208:211], v[50:53]
	v_mfma_f32_16x16x32_bf16 v[42:45], v[168:171], v[204:207], v[42:45]
	v_mfma_f32_16x16x32_bf16 v[42:45], v[172:175], v[208:211], v[42:45]
	v_mfma_f32_16x16x32_bf16 v[34:37], v[160:163], v[212:215], v[34:37]
	v_mfma_f32_16x16x32_bf16 v[34:37], v[164:167], v[216:219], v[34:37]
	v_mfma_f32_16x16x32_bf16 v[26:29], v[168:171], v[212:215], v[26:29]
	v_mfma_f32_16x16x32_bf16 v[26:29], v[172:175], v[216:219], v[26:29]
	v_mfma_f32_16x16x32_bf16 v[18:21], v[160:163], v[220:223], v[18:21]
	v_mfma_f32_16x16x32_bf16 v[18:21], v[164:167], v[224:227], v[18:21]
	v_mfma_f32_16x16x32_bf16 v[10:13], v[168:171], v[220:223], v[10:13]
	v_mfma_f32_16x16x32_bf16 v[10:13], v[172:175], v[224:227], v[10:13]
	s_setprio 0
	s_setprio 1
	v_mfma_f32_16x16x32_bf16 v[54:57], v[176:179], v[196:199], v[54:57]
	v_mfma_f32_16x16x32_bf16 v[54:57], v[184:187], v[200:203], v[54:57]
	v_mfma_f32_16x16x32_bf16 v[46:49], v[188:191], v[196:199], v[46:49]
	v_mfma_f32_16x16x32_bf16 v[46:49], v[192:195], v[200:203], v[46:49]
	v_mfma_f32_16x16x32_bf16 v[38:41], v[176:179], v[204:207], v[38:41]
	v_mfma_f32_16x16x32_bf16 v[38:41], v[184:187], v[208:211], v[38:41]
	v_mfma_f32_16x16x32_bf16 v[30:33], v[188:191], v[204:207], v[30:33]
	v_mfma_f32_16x16x32_bf16 v[30:33], v[192:195], v[208:211], v[30:33]
	v_mfma_f32_16x16x32_bf16 v[22:25], v[176:179], v[212:215], v[22:25]
	v_mfma_f32_16x16x32_bf16 v[22:25], v[184:187], v[216:219], v[22:25]
	v_mfma_f32_16x16x32_bf16 v[14:17], v[188:191], v[212:215], v[14:17]
	v_mfma_f32_16x16x32_bf16 v[14:17], v[192:195], v[216:219], v[14:17]
	v_mfma_f32_16x16x32_bf16 v[6:9], v[176:179], v[220:223], v[6:9]
	v_mfma_f32_16x16x32_bf16 v[6:9], v[184:187], v[224:227], v[6:9]
	v_mfma_f32_16x16x32_bf16 v[2:5], v[188:191], v[220:223], v[2:5]
	v_mfma_f32_16x16x32_bf16 v[2:5], v[192:195], v[224:227], v[2:5]
	s_setprio 0
	s_barrier
	s_add_i32 s89, s89, 2
	s_add_u32 s6, s6, 0x100
	s_addc_u32 s7, s7, 0
	s_add_u32 s87, s87, 0x100
	s_addc_u32 s88, s88, 0
	s_cmp_gt_u32 s89, 61
	s_cbranch_scc0 .LBB0_2494
	s_and_b64 vcc, exec, s[38:39]
	s_cbranch_vccz .LBB0_2497
	s_barrier

.LBB0_2635:
	ds_read_b128 v[130:133], v163
	ds_read_b128 v[134:137], v163 offset:1024
	ds_read_b128 v[138:141], v163 offset:2048
	ds_read_b128 v[142:145], v163 offset:3072
	ds_read_b128 v[146:149], v188
	ds_read_b128 v[150:153], v188 offset:1024
	ds_read_b128 v[174:177], v188 offset:2048
	ds_read_b128 v[178:181], v188 offset:3072
	s_add_u32 s48, s46, 0xfff00080
	s_addc_u32 s49, s47, -1
	s_cmp_eq_u32 s73, 60
	s_cselect_b32 s51, s22, s49
	s_cselect_b32 s50, s41, s48
	s_cselect_b32 s49, s39, s72
	s_cselect_b32 s48, s70, s71
	v_lshl_add_u64 v[220:221], s[46:47], 0, v[166:167]
	s_add_i32 m0, s13, 0xc000
	ds_read_b128 v[184:187], v189
	ds_read_b128 v[192:195], v189 offset:1024
	ds_read_b128 v[196:199], v189 offset:2048
	ds_read_b128 v[200:203], v189 offset:3072
	ds_read_b128 v[204:207], v189 offset:4096
	ds_read_b128 v[208:211], v189 offset:5120
	ds_read_b128 v[212:215], v189 offset:6144
	ds_read_b128 v[216:219], v189 offset:7168
	global_load_lds_dwordx4 v[220:221], off
	v_lshl_add_u64 v[220:221], s[46:47], 0, v[168:169]
	s_add_i32 m0, s13, 0xe000
	s_nop 0
	global_load_lds_dwordx4 v[220:221], off
	s_waitcnt vmcnt(8)
	s_waitcnt lgkmcnt(0)
	s_barrier
	s_setprio 1
	s_waitcnt lgkmcnt(0)
	v_mfma_f32_16x16x32_bf16 v[126:129], v[130:133], v[184:187], v[126:129]
	v_mfma_f32_16x16x32_bf16 v[126:129], v[134:137], v[192:195], v[126:129]
	v_mfma_f32_16x16x32_bf16 v[122:125], v[138:141], v[184:187], v[122:125]
	v_mfma_f32_16x16x32_bf16 v[122:125], v[142:145], v[192:195], v[122:125]
	v_mfma_f32_16x16x32_bf16 v[110:113], v[130:133], v[196:199], v[110:113]
	v_mfma_f32_16x16x32_bf16 v[110:113], v[134:137], v[200:203], v[110:113]
	v_mfma_f32_16x16x32_bf16 v[106:109], v[138:141], v[196:199], v[106:109]
	v_mfma_f32_16x16x32_bf16 v[106:109], v[142:145], v[200:203], v[106:109]
	v_mfma_f32_16x16x32_bf16 v[94:97], v[130:133], v[204:207], v[94:97]
	v_mfma_f32_16x16x32_bf16 v[94:97], v[134:137], v[208:211], v[94:97]
	v_mfma_f32_16x16x32_bf16 v[90:93], v[138:141], v[204:207], v[90:93]
	v_mfma_f32_16x16x32_bf16 v[90:93], v[142:145], v[208:211], v[90:93]
	v_mfma_f32_16x16x32_bf16 v[78:81], v[130:133], v[212:215], v[78:81]
	v_mfma_f32_16x16x32_bf16 v[78:81], v[134:137], v[216:219], v[78:81]
	v_mfma_f32_16x16x32_bf16 v[74:77], v[138:141], v[212:215], v[74:77]
	v_mfma_f32_16x16x32_bf16 v[74:77], v[142:145], v[216:219], v[74:77]
	s_setprio 0
	s_setprio 1
	v_mfma_f32_16x16x32_bf16 v[118:121], v[146:149], v[184:187], v[118:121]
	v_mfma_f32_16x16x32_bf16 v[118:121], v[150:153], v[192:195], v[118:121]
	v_mfma_f32_16x16x32_bf16 v[114:117], v[174:177], v[184:187], v[114:117]
	v_mfma_f32_16x16x32_bf16 v[114:117], v[178:181], v[192:195], v[114:117]
	v_mfma_f32_16x16x32_bf16 v[102:105], v[146:149], v[196:199], v[102:105]
	v_mfma_f32_16x16x32_bf16 v[102:105], v[150:153], v[200:203], v[102:105]
	v_mfma_f32_16x16x32_bf16 v[98:101], v[174:177], v[196:199], v[98:101]
	v_mfma_f32_16x16x32_bf16 v[98:101], v[178:181], v[200:203], v[98:101]
	v_mfma_f32_16x16x32_bf16 v[86:89], v[146:149], v[204:207], v[86:89]
	v_mfma_f32_16x16x32_bf16 v[86:89], v[150:153], v[208:211], v[86:89]
	v_mfma_f32_16x16x32_bf16 v[82:85], v[174:177], v[204:207], v[82:85]
	v_mfma_f32_16x16x32_bf16 v[82:85], v[178:181], v[208:211], v[82:85]
	v_mfma_f32_16x16x32_bf16 v[70:73], v[146:149], v[212:215], v[70:73]
	v_mfma_f32_16x16x32_bf16 v[70:73], v[150:153], v[216:219], v[70:73]
	v_mfma_f32_16x16x32_bf16 v[66:69], v[174:177], v[212:215], v[66:69]
	v_mfma_f32_16x16x32_bf16 v[66:69], v[178:181], v[216:219], v[66:69]
	s_setprio 0
	s_barrier
	s_add_i32 s74, s67, s3
	v_lshl_add_u64 v[220:221], s[48:49], 0, v[156:157]
	s_mov_b32 m0, s74
	ds_read_b128 v[184:187], v189 offset:16384
	ds_read_b128 v[192:195], v189 offset:17408
	ds_read_b128 v[196:199], v189 offset:18432
	ds_read_b128 v[200:203], v189 offset:19456
	ds_read_b128 v[204:207], v189 offset:20480
	ds_read_b128 v[208:211], v189 offset:21504
	ds_read_b128 v[212:215], v189 offset:22528
	ds_read_b128 v[216:219], v189 offset:23552
	global_load_lds_dwordx4 v[220:221], off
	s_add_i32 m0, s74, 0x2000
	s_add_u32 s74, s48, 0x100000
	v_lshl_add_u64 v[222:223], s[48:49], 0, v[160:161]
	s_addc_u32 s75, s49, 0
	s_add_i32 s76, s68, s3
	global_load_lds_dwordx4 v[222:223], off
	v_lshl_add_u64 v[224:225], s[74:75], 0, v[156:157]
	s_mov_b32 m0, s76
	v_lshl_add_u64 v[226:227], s[50:51], 0, v[158:159]
	global_load_lds_dwordx4 v[224:225], off
	v_lshl_add_u64 v[224:225], s[74:75], 0, v[160:161]
	s_add_i32 m0, s76, 0x2000
	s_nop 0
	global_load_lds_dwordx4 v[224:225], off
	v_lshl_add_u64 v[224:225], s[50:51], 0, v[154:155]
	s_mov_b32 m0, s13
	s_nop 0
	global_load_lds_dwordx4 v[224:225], off
	s_mov_b32 m0, s21
	s_nop 0
	global_load_lds_dwordx4 v[226:227], off
	s_waitcnt vmcnt(8)
	s_waitcnt lgkmcnt(0)
	s_barrier
	s_setprio 1
	s_waitcnt lgkmcnt(0)
	v_mfma_f32_16x16x32_bf16 v[62:65], v[130:133], v[184:187], v[62:65]
	v_mfma_f32_16x16x32_bf16 v[62:65], v[134:137], v[192:195], v[62:65]
	v_mfma_f32_16x16x32_bf16 v[58:61], v[138:141], v[184:187], v[58:61]
	v_mfma_f32_16x16x32_bf16 v[58:61], v[142:145], v[192:195], v[58:61]
	v_mfma_f32_16x16x32_bf16 v[46:49], v[130:133], v[196:199], v[46:49]
	v_mfma_f32_16x16x32_bf16 v[46:49], v[134:137], v[200:203], v[46:49]
	v_mfma_f32_16x16x32_bf16 v[42:45], v[138:141], v[196:199], v[42:45]
	v_mfma_f32_16x16x32_bf16 v[42:45], v[142:145], v[200:203], v[42:45]
	v_mfma_f32_16x16x32_bf16 v[30:33], v[130:133], v[204:207], v[30:33]
	v_mfma_f32_16x16x32_bf16 v[30:33], v[134:137], v[208:211], v[30:33]
	v_mfma_f32_16x16x32_bf16 v[26:29], v[138:141], v[204:207], v[26:29]
	v_mfma_f32_16x16x32_bf16 v[26:29], v[142:145], v[208:211], v[26:29]
	v_mfma_f32_16x16x32_bf16 v[14:17], v[130:133], v[212:215], v[14:17]
	v_mfma_f32_16x16x32_bf16 v[14:17], v[134:137], v[216:219], v[14:17]
	v_mfma_f32_16x16x32_bf16 v[10:13], v[138:141], v[212:215], v[10:13]
	v_mfma_f32_16x16x32_bf16 v[10:13], v[142:145], v[216:219], v[10:13]
	s_setprio 0
	s_setprio 1
	v_mfma_f32_16x16x32_bf16 v[54:57], v[146:149], v[184:187], v[54:57]
	v_mfma_f32_16x16x32_bf16 v[54:57], v[150:153], v[192:195], v[54:57]
	v_mfma_f32_16x16x32_bf16 v[50:53], v[174:177], v[184:187], v[50:53]
	v_mfma_f32_16x16x32_bf16 v[50:53], v[178:181], v[192:195], v[50:53]
	v_mfma_f32_16x16x32_bf16 v[38:41], v[146:149], v[196:199], v[38:41]
	v_mfma_f32_16x16x32_bf16 v[38:41], v[150:153], v[200:203], v[38:41]
	v_mfma_f32_16x16x32_bf16 v[34:37], v[174:177], v[196:199], v[34:37]
	v_mfma_f32_16x16x32_bf16 v[34:37], v[178:181], v[200:203], v[34:37]
	v_mfma_f32_16x16x32_bf16 v[22:25], v[146:149], v[204:207], v[22:25]
	v_mfma_f32_16x16x32_bf16 v[22:25], v[150:153], v[208:211], v[22:25]
	v_mfma_f32_16x16x32_bf16 v[18:21], v[174:177], v[204:207], v[18:21]
	v_mfma_f32_16x16x32_bf16 v[18:21], v[178:181], v[208:211], v[18:21]
	v_mfma_f32_16x16x32_bf16 v[6:9], v[146:149], v[212:215], v[6:9]
	v_mfma_f32_16x16x32_bf16 v[6:9], v[150:153], v[216:219], v[6:9]
	v_mfma_f32_16x16x32_bf16 v[2:5], v[174:177], v[212:215], v[2:5]
	v_mfma_f32_16x16x32_bf16 v[2:5], v[178:181], v[216:219], v[2:5]
	s_setprio 0
	s_barrier
	s_add_i32 s74, 0, 0x18000
	s_add_i32 s75, 0, 0x1c000
	v_add_u32_e32 v142, s74, v1
	v_add_u32_e32 v178, s75, v1
	ds_read_b128 v[130:133], v142
	ds_read_b128 v[134:137], v142 offset:1024
	ds_read_b128 v[138:141], v142 offset:2048
	ds_read_b128 v[142:145], v142 offset:3072
	ds_read_b128 v[146:149], v178
	ds_read_b128 v[150:153], v178 offset:1024
	ds_read_b128 v[174:177], v178 offset:2048
	ds_read_b128 v[178:181], v178 offset:3072
	s_add_u32 s50, s50, 0x100000
	s_addc_u32 s51, s51, 0
	s_mov_b32 m0, s33
	v_lshl_add_u64 v[228:229], s[50:51], 0, v[154:155]
	ds_read_b128 v[184:187], v189 offset:32768
	ds_read_b128 v[192:195], v189 offset:33792
	ds_read_b128 v[196:199], v189 offset:34816
	ds_read_b128 v[200:203], v189 offset:35840
	ds_read_b128 v[204:207], v189 offset:36864
	ds_read_b128 v[208:211], v189 offset:37888
	ds_read_b128 v[212:215], v189 offset:38912
	ds_read_b128 v[216:219], v189 offset:39936
	global_load_lds_dwordx4 v[228:229], off
	v_lshl_add_u64 v[228:229], s[50:51], 0, v[158:159]
	s_mov_b32 m0, s35
	s_nop 0
	global_load_lds_dwordx4 v[228:229], off
	s_waitcnt vmcnt(8)
	s_waitcnt lgkmcnt(0)
	s_barrier
	s_setprio 1
	s_waitcnt lgkmcnt(0)
	v_mfma_f32_16x16x32_bf16 v[126:129], v[130:133], v[184:187], v[126:129]
	v_mfma_f32_16x16x32_bf16 v[126:129], v[134:137], v[192:195], v[126:129]
	v_mfma_f32_16x16x32_bf16 v[122:125], v[138:141], v[184:187], v[122:125]
	v_mfma_f32_16x16x32_bf16 v[122:125], v[142:145], v[192:195], v[122:125]
	v_mfma_f32_16x16x32_bf16 v[110:113], v[130:133], v[196:199], v[110:113]
	v_mfma_f32_16x16x32_bf16 v[110:113], v[134:137], v[200:203], v[110:113]
	v_mfma_f32_16x16x32_bf16 v[106:109], v[138:141], v[196:199], v[106:109]
	v_mfma_f32_16x16x32_bf16 v[106:109], v[142:145], v[200:203], v[106:109]
	v_mfma_f32_16x16x32_bf16 v[94:97], v[130:133], v[204:207], v[94:97]
	v_mfma_f32_16x16x32_bf16 v[94:97], v[134:137], v[208:211], v[94:97]
	v_mfma_f32_16x16x32_bf16 v[90:93], v[138:141], v[204:207], v[90:93]
	v_mfma_f32_16x16x32_bf16 v[90:93], v[142:145], v[208:211], v[90:93]
	v_mfma_f32_16x16x32_bf16 v[78:81], v[130:133], v[212:215], v[78:81]
	v_mfma_f32_16x16x32_bf16 v[78:81], v[134:137], v[216:219], v[78:81]
	v_mfma_f32_16x16x32_bf16 v[74:77], v[138:141], v[212:215], v[74:77]
	v_mfma_f32_16x16x32_bf16 v[74:77], v[142:145], v[216:219], v[74:77]
	s_setprio 0
	s_setprio 1
	v_mfma_f32_16x16x32_bf16 v[118:121], v[146:149], v[184:187], v[118:121]
	v_mfma_f32_16x16x32_bf16 v[118:121], v[150:153], v[192:195], v[118:121]
	v_mfma_f32_16x16x32_bf16 v[114:117], v[174:177], v[184:187], v[114:117]
	v_mfma_f32_16x16x32_bf16 v[114:117], v[178:181], v[192:195], v[114:117]
	v_mfma_f32_16x16x32_bf16 v[102:105], v[146:149], v[196:199], v[102:105]
	v_mfma_f32_16x16x32_bf16 v[102:105], v[150:153], v[200:203], v[102:105]
	v_mfma_f32_16x16x32_bf16 v[98:101], v[174:177], v[196:199], v[98:101]
	v_mfma_f32_16x16x32_bf16 v[98:101], v[178:181], v[200:203], v[98:101]
	v_mfma_f32_16x16x32_bf16 v[86:89], v[146:149], v[204:207], v[86:89]
	v_mfma_f32_16x16x32_bf16 v[86:89], v[150:153], v[208:211], v[86:89]
	v_mfma_f32_16x16x32_bf16 v[82:85], v[174:177], v[204:207], v[82:85]
	v_mfma_f32_16x16x32_bf16 v[82:85], v[178:181], v[208:211], v[82:85]
	v_mfma_f32_16x16x32_bf16 v[70:73], v[146:149], v[212:215], v[70:73]
	v_mfma_f32_16x16x32_bf16 v[70:73], v[150:153], v[216:219], v[70:73]
	v_mfma_f32_16x16x32_bf16 v[66:69], v[174:177], v[212:215], v[66:69]
	v_mfma_f32_16x16x32_bf16 v[66:69], v[178:181], v[216:219], v[66:69]
	s_setprio 0
	s_barrier
	s_add_i32 s50, s74, s3
	v_lshl_add_u64 v[220:221], v[220:221], 0, s[28:29]
	s_mov_b32 m0, s50
	ds_read_b128 v[184:187], v189 offset:49152
	ds_read_b128 v[192:195], v189 offset:50176
	ds_read_b128 v[196:199], v189 offset:51200
	ds_read_b128 v[200:203], v189 offset:52224
	ds_read_b128 v[204:207], v189 offset:53248
	ds_read_b128 v[208:211], v189 offset:54272
	ds_read_b128 v[212:215], v189 offset:55296
	ds_read_b128 v[216:219], v189 offset:56320
	global_load_lds_dwordx4 v[220:221], off
	s_add_i32 m0, s50, 0x2000
	s_add_u32 s48, s48, 0x100080
	v_lshl_add_u64 v[220:221], v[222:223], 0, s[28:29]
	s_addc_u32 s49, s49, 0
	s_add_i32 s50, s75, s3
	global_load_lds_dwordx4 v[220:221], off
	v_lshl_add_u64 v[220:221], s[48:49], 0, v[156:157]
	s_mov_b32 m0, s50
	s_nop 0
	global_load_lds_dwordx4 v[220:221], off
	v_lshl_add_u64 v[220:221], s[48:49], 0, v[160:161]
	s_add_i32 m0, s50, 0x2000
	s_nop 0
	global_load_lds_dwordx4 v[220:221], off
	v_lshl_add_u64 v[220:221], v[224:225], 0, s[28:29]
	s_mov_b32 m0, s62
	s_nop 0
	global_load_lds_dwordx4 v[220:221], off
	v_lshl_add_u64 v[220:221], v[226:227], 0, s[28:29]
	s_mov_b32 m0, s63
	s_nop 0
	global_load_lds_dwordx4 v[220:221], off
	s_waitcnt vmcnt(8)
	s_waitcnt lgkmcnt(0)
	s_barrier
	s_setprio 1
	s_waitcnt lgkmcnt(0)
	v_mfma_f32_16x16x32_bf16 v[62:65], v[130:133], v[184:187], v[62:65]
	v_mfma_f32_16x16x32_bf16 v[62:65], v[134:137], v[192:195], v[62:65]
	v_mfma_f32_16x16x32_bf16 v[58:61], v[138:141], v[184:187], v[58:61]
	v_mfma_f32_16x16x32_bf16 v[58:61], v[142:145], v[192:195], v[58:61]
	v_mfma_f32_16x16x32_bf16 v[46:49], v[130:133], v[196:199], v[46:49]
	v_mfma_f32_16x16x32_bf16 v[46:49], v[134:137], v[200:203], v[46:49]
	v_mfma_f32_16x16x32_bf16 v[42:45], v[138:141], v[196:199], v[42:45]
	v_mfma_f32_16x16x32_bf16 v[42:45], v[142:145], v[200:203], v[42:45]
	v_mfma_f32_16x16x32_bf16 v[30:33], v[130:133], v[204:207], v[30:33]
	v_mfma_f32_16x16x32_bf16 v[30:33], v[134:137], v[208:211], v[30:33]
	v_mfma_f32_16x16x32_bf16 v[26:29], v[138:141], v[204:207], v[26:29]
	v_mfma_f32_16x16x32_bf16 v[26:29], v[142:145], v[208:211], v[26:29]
	v_mfma_f32_16x16x32_bf16 v[14:17], v[130:133], v[212:215], v[14:17]
	v_mfma_f32_16x16x32_bf16 v[14:17], v[134:137], v[216:219], v[14:17]
	v_mfma_f32_16x16x32_bf16 v[10:13], v[138:141], v[212:215], v[10:13]
	v_mfma_f32_16x16x32_bf16 v[10:13], v[142:145], v[216:219], v[10:13]
	s_setprio 0
	s_setprio 1
	v_mfma_f32_16x16x32_bf16 v[54:57], v[146:149], v[184:187], v[54:57]
	v_mfma_f32_16x16x32_bf16 v[54:57], v[150:153], v[192:195], v[54:57]
	v_mfma_f32_16x16x32_bf16 v[50:53], v[174:177], v[184:187], v[50:53]
	v_mfma_f32_16x16x32_bf16 v[50:53], v[178:181], v[192:195], v[50:53]
	v_mfma_f32_16x16x32_bf16 v[38:41], v[146:149], v[196:199], v[38:41]
	v_mfma_f32_16x16x32_bf16 v[38:41], v[150:153], v[200:203], v[38:41]
	v_mfma_f32_16x16x32_bf16 v[34:37], v[174:177], v[196:199], v[34:37]
	v_mfma_f32_16x16x32_bf16 v[34:37], v[178:181], v[200:203], v[34:37]
	v_mfma_f32_16x16x32_bf16 v[22:25], v[146:149], v[204:207], v[22:25]
	v_mfma_f32_16x16x32_bf16 v[22:25], v[150:153], v[208:211], v[22:25]
	v_mfma_f32_16x16x32_bf16 v[18:21], v[174:177], v[204:207], v[18:21]
	v_mfma_f32_16x16x32_bf16 v[18:21], v[178:181], v[208:211], v[18:21]
	v_mfma_f32_16x16x32_bf16 v[6:9], v[146:149], v[212:215], v[6:9]
	v_mfma_f32_16x16x32_bf16 v[6:9], v[150:153], v[216:219], v[6:9]
	v_mfma_f32_16x16x32_bf16 v[2:5], v[174:177], v[212:215], v[2:5]
	v_mfma_f32_16x16x32_bf16 v[2:5], v[178:181], v[216:219], v[2:5]
	s_setprio 0
	s_barrier
	s_add_i32 s73, s73, 2
	s_add_u32 s46, s46, 0x100
	s_addc_u32 s47, s47, 0
	s_add_u32 s71, s71, 0x100
	s_addc_u32 s72, s72, 0
	s_cmp_gt_u32 s73, 61
	s_cbranch_scc0 .LBB0_2635
	s_and_b64 vcc, exec, s[36:37]
	s_cbranch_vccz .LBB0_2638
	s_barrier

.LBB0_2720:
	ds_read_b128 v[148:151], v159
	ds_read_b128 v[164:167], v159 offset:1024
	ds_read_b128 v[168:171], v159 offset:2048
	ds_read_b128 v[172:175], v159 offset:3072
	ds_read_b128 v[176:179], v160
	ds_read_b128 v[184:187], v160 offset:1024
	ds_read_b128 v[188:191], v160 offset:2048
	ds_read_b128 v[192:195], v160 offset:3072
	s_add_u32 s40, s6, 0xfff00080
	s_addc_u32 s41, s7, -1
	s_cmp_eq_u32 s82, 60
	s_cselect_b32 s43, s29, s41
	s_cselect_b32 s42, s78, s40
	s_cselect_b32 s41, s27, s81
	s_cselect_b32 s40, s79, s80
	v_lshl_add_u64 v[152:153], s[6:7], 0, v[140:141]
	s_add_i32 m0, s44, 0xc000
	ds_read_b128 v[196:199], v161
	ds_read_b128 v[200:203], v161 offset:1024
	ds_read_b128 v[204:207], v161 offset:2048
	ds_read_b128 v[208:211], v161 offset:3072
	ds_read_b128 v[212:215], v161 offset:4096
	ds_read_b128 v[216:219], v161 offset:5120
	ds_read_b128 v[220:223], v161 offset:6144
	ds_read_b128 v[224:227], v161 offset:7168
	global_load_lds_dwordx4 v[152:153], off
	v_lshl_add_u64 v[152:153], s[6:7], 0, v[142:143]
	s_add_i32 m0, s44, 0xe000
	s_nop 0
	global_load_lds_dwordx4 v[152:153], off
	s_waitcnt vmcnt(8)
	s_waitcnt lgkmcnt(0)
	s_barrier
	s_setprio 1
	s_waitcnt lgkmcnt(0)
	v_mfma_f32_16x16x32_bf16 v[126:129], v[148:151], v[196:199], v[126:129]
	v_mfma_f32_16x16x32_bf16 v[126:129], v[164:167], v[200:203], v[126:129]
	v_mfma_f32_16x16x32_bf16 v[118:121], v[168:171], v[196:199], v[118:121]
	v_mfma_f32_16x16x32_bf16 v[118:121], v[172:175], v[200:203], v[118:121]
	v_mfma_f32_16x16x32_bf16 v[110:113], v[148:151], v[204:207], v[110:113]
	v_mfma_f32_16x16x32_bf16 v[110:113], v[164:167], v[208:211], v[110:113]
	v_mfma_f32_16x16x32_bf16 v[102:105], v[168:171], v[204:207], v[102:105]
	v_mfma_f32_16x16x32_bf16 v[102:105], v[172:175], v[208:211], v[102:105]
	v_mfma_f32_16x16x32_bf16 v[94:97], v[148:151], v[212:215], v[94:97]
	v_mfma_f32_16x16x32_bf16 v[94:97], v[164:167], v[216:219], v[94:97]
	v_mfma_f32_16x16x32_bf16 v[86:89], v[168:171], v[212:215], v[86:89]
	v_mfma_f32_16x16x32_bf16 v[86:89], v[172:175], v[216:219], v[86:89]
	v_mfma_f32_16x16x32_bf16 v[78:81], v[148:151], v[220:223], v[78:81]
	v_mfma_f32_16x16x32_bf16 v[78:81], v[164:167], v[224:227], v[78:81]
	v_mfma_f32_16x16x32_bf16 v[70:73], v[168:171], v[220:223], v[70:73]
	v_mfma_f32_16x16x32_bf16 v[70:73], v[172:175], v[224:227], v[70:73]
	s_setprio 0
	s_setprio 1
	v_mfma_f32_16x16x32_bf16 v[122:125], v[176:179], v[196:199], v[122:125]
	v_mfma_f32_16x16x32_bf16 v[122:125], v[184:187], v[200:203], v[122:125]
	v_mfma_f32_16x16x32_bf16 v[114:117], v[188:191], v[196:199], v[114:117]
	v_mfma_f32_16x16x32_bf16 v[114:117], v[192:195], v[200:203], v[114:117]
	v_mfma_f32_16x16x32_bf16 v[106:109], v[176:179], v[204:207], v[106:109]
	v_mfma_f32_16x16x32_bf16 v[106:109], v[184:187], v[208:211], v[106:109]
	v_mfma_f32_16x16x32_bf16 v[98:101], v[188:191], v[204:207], v[98:101]
	v_mfma_f32_16x16x32_bf16 v[98:101], v[192:195], v[208:211], v[98:101]
	v_mfma_f32_16x16x32_bf16 v[90:93], v[176:179], v[212:215], v[90:93]
	v_mfma_f32_16x16x32_bf16 v[90:93], v[184:187], v[216:219], v[90:93]
	v_mfma_f32_16x16x32_bf16 v[82:85], v[188:191], v[212:215], v[82:85]
	v_mfma_f32_16x16x32_bf16 v[82:85], v[192:195], v[216:219], v[82:85]
	v_mfma_f32_16x16x32_bf16 v[74:77], v[176:179], v[220:223], v[74:77]
	v_mfma_f32_16x16x32_bf16 v[74:77], v[184:187], v[224:227], v[74:77]
	v_mfma_f32_16x16x32_bf16 v[66:69], v[188:191], v[220:223], v[66:69]
	v_mfma_f32_16x16x32_bf16 v[66:69], v[192:195], v[224:227], v[66:69]
	s_setprio 0
	s_barrier
	s_add_i32 s83, s68, s13
	v_lshl_add_u64 v[152:153], s[40:41], 0, v[132:133]
	s_mov_b32 m0, s83
	ds_read_b128 v[196:199], v161 offset:16384
	ds_read_b128 v[200:203], v161 offset:17408
	ds_read_b128 v[204:207], v161 offset:18432
	ds_read_b128 v[208:211], v161 offset:19456
	ds_read_b128 v[212:215], v161 offset:20480
	ds_read_b128 v[216:219], v161 offset:21504
	ds_read_b128 v[220:223], v161 offset:22528
	ds_read_b128 v[224:227], v161 offset:23552
	global_load_lds_dwordx4 v[152:153], off
	s_add_i32 m0, s83, 0x2000
	s_add_u32 s84, s40, 0x100000
	v_lshl_add_u64 v[180:181], s[40:41], 0, v[136:137]
	s_addc_u32 s85, s41, 0
	s_add_i32 s83, s69, s13
	global_load_lds_dwordx4 v[180:181], off
	v_lshl_add_u64 v[228:229], s[84:85], 0, v[132:133]
	s_mov_b32 m0, s83
	v_lshl_add_u64 v[230:231], s[42:43], 0, v[134:135]
	global_load_lds_dwordx4 v[228:229], off
	v_lshl_add_u64 v[228:229], s[84:85], 0, v[136:137]
	s_add_i32 m0, s83, 0x2000
	s_nop 0
	global_load_lds_dwordx4 v[228:229], off
	v_lshl_add_u64 v[228:229], s[42:43], 0, v[130:131]
	s_mov_b32 m0, s44
	s_nop 0
	global_load_lds_dwordx4 v[228:229], off
	s_mov_b32 m0, s45
	s_nop 0
	global_load_lds_dwordx4 v[230:231], off
	s_waitcnt vmcnt(8)
	s_waitcnt lgkmcnt(0)
	s_barrier
	s_setprio 1
	s_waitcnt lgkmcnt(0)
	v_mfma_f32_16x16x32_bf16 v[62:65], v[148:151], v[196:199], v[62:65]
	v_mfma_f32_16x16x32_bf16 v[62:65], v[164:167], v[200:203], v[62:65]
	v_mfma_f32_16x16x32_bf16 v[54:57], v[168:171], v[196:199], v[54:57]
	v_mfma_f32_16x16x32_bf16 v[54:57], v[172:175], v[200:203], v[54:57]
	v_mfma_f32_16x16x32_bf16 v[46:49], v[148:151], v[204:207], v[46:49]
	v_mfma_f32_16x16x32_bf16 v[46:49], v[164:167], v[208:211], v[46:49]
	v_mfma_f32_16x16x32_bf16 v[38:41], v[168:171], v[204:207], v[38:41]
	v_mfma_f32_16x16x32_bf16 v[38:41], v[172:175], v[208:211], v[38:41]
	v_mfma_f32_16x16x32_bf16 v[30:33], v[148:151], v[212:215], v[30:33]
	v_mfma_f32_16x16x32_bf16 v[30:33], v[164:167], v[216:219], v[30:33]
	v_mfma_f32_16x16x32_bf16 v[22:25], v[168:171], v[212:215], v[22:25]
	v_mfma_f32_16x16x32_bf16 v[22:25], v[172:175], v[216:219], v[22:25]
	v_mfma_f32_16x16x32_bf16 v[14:17], v[148:151], v[220:223], v[14:17]
	v_mfma_f32_16x16x32_bf16 v[14:17], v[164:167], v[224:227], v[14:17]
	v_mfma_f32_16x16x32_bf16 v[6:9], v[168:171], v[220:223], v[6:9]
	v_mfma_f32_16x16x32_bf16 v[6:9], v[172:175], v[224:227], v[6:9]
	s_setprio 0
	s_setprio 1
	v_mfma_f32_16x16x32_bf16 v[58:61], v[176:179], v[196:199], v[58:61]
	v_mfma_f32_16x16x32_bf16 v[58:61], v[184:187], v[200:203], v[58:61]
	v_mfma_f32_16x16x32_bf16 v[50:53], v[188:191], v[196:199], v[50:53]
	v_mfma_f32_16x16x32_bf16 v[50:53], v[192:195], v[200:203], v[50:53]
	v_mfma_f32_16x16x32_bf16 v[42:45], v[176:179], v[204:207], v[42:45]
	v_mfma_f32_16x16x32_bf16 v[42:45], v[184:187], v[208:211], v[42:45]
	v_mfma_f32_16x16x32_bf16 v[34:37], v[188:191], v[204:207], v[34:37]
	v_mfma_f32_16x16x32_bf16 v[34:37], v[192:195], v[208:211], v[34:37]
	v_mfma_f32_16x16x32_bf16 v[26:29], v[176:179], v[212:215], v[26:29]
	v_mfma_f32_16x16x32_bf16 v[26:29], v[184:187], v[216:219], v[26:29]
	v_mfma_f32_16x16x32_bf16 v[18:21], v[188:191], v[212:215], v[18:21]
	v_mfma_f32_16x16x32_bf16 v[18:21], v[192:195], v[216:219], v[18:21]
	v_mfma_f32_16x16x32_bf16 v[10:13], v[176:179], v[220:223], v[10:13]
	v_mfma_f32_16x16x32_bf16 v[10:13], v[184:187], v[224:227], v[10:13]
	v_mfma_f32_16x16x32_bf16 v[2:5], v[188:191], v[220:223], v[2:5]
	v_mfma_f32_16x16x32_bf16 v[2:5], v[192:195], v[224:227], v[2:5]
	s_setprio 0
	s_barrier
	s_add_i32 s83, 0, 0x18000
	v_add_u32_e32 v138, s83, v155
	s_add_i32 s84, 0, 0x1c000
	ds_read_b128 v[148:151], v138
	ds_read_b128 v[164:167], v138 offset:1024
	ds_read_b128 v[168:171], v138 offset:2048
	ds_read_b128 v[172:175], v138 offset:3072
	v_add_u32_e32 v138, s84, v155
	ds_read_b128 v[176:179], v138
	ds_read_b128 v[184:187], v138 offset:1024
	ds_read_b128 v[188:191], v138 offset:2048
	ds_read_b128 v[192:195], v138 offset:3072
	s_add_u32 s42, s42, 0x100000
	s_addc_u32 s43, s43, 0
	s_mov_b32 m0, s46
	v_lshl_add_u64 v[232:233], s[42:43], 0, v[130:131]
	ds_read_b128 v[196:199], v161 offset:32768
	ds_read_b128 v[200:203], v161 offset:33792
	ds_read_b128 v[204:207], v161 offset:34816
	ds_read_b128 v[208:211], v161 offset:35840
	ds_read_b128 v[212:215], v161 offset:36864
	ds_read_b128 v[216:219], v161 offset:37888
	ds_read_b128 v[220:223], v161 offset:38912
	ds_read_b128 v[224:227], v161 offset:39936
	global_load_lds_dwordx4 v[232:233], off
	v_lshl_add_u64 v[232:233], s[42:43], 0, v[134:135]
	s_mov_b32 m0, s47
	s_nop 0
	global_load_lds_dwordx4 v[232:233], off
	s_waitcnt vmcnt(8)
	s_waitcnt lgkmcnt(0)
	s_barrier
	s_setprio 1
	s_waitcnt lgkmcnt(0)
	v_mfma_f32_16x16x32_bf16 v[126:129], v[148:151], v[196:199], v[126:129]
	v_mfma_f32_16x16x32_bf16 v[126:129], v[164:167], v[200:203], v[126:129]
	v_mfma_f32_16x16x32_bf16 v[118:121], v[168:171], v[196:199], v[118:121]
	v_mfma_f32_16x16x32_bf16 v[118:121], v[172:175], v[200:203], v[118:121]
	v_mfma_f32_16x16x32_bf16 v[110:113], v[148:151], v[204:207], v[110:113]
	v_mfma_f32_16x16x32_bf16 v[110:113], v[164:167], v[208:211], v[110:113]
	v_mfma_f32_16x16x32_bf16 v[102:105], v[168:171], v[204:207], v[102:105]
	v_mfma_f32_16x16x32_bf16 v[102:105], v[172:175], v[208:211], v[102:105]
	v_mfma_f32_16x16x32_bf16 v[94:97], v[148:151], v[212:215], v[94:97]
	v_mfma_f32_16x16x32_bf16 v[94:97], v[164:167], v[216:219], v[94:97]
	v_mfma_f32_16x16x32_bf16 v[86:89], v[168:171], v[212:215], v[86:89]
	v_mfma_f32_16x16x32_bf16 v[86:89], v[172:175], v[216:219], v[86:89]
	v_mfma_f32_16x16x32_bf16 v[78:81], v[148:151], v[220:223], v[78:81]
	v_mfma_f32_16x16x32_bf16 v[78:81], v[164:167], v[224:227], v[78:81]
	v_mfma_f32_16x16x32_bf16 v[70:73], v[168:171], v[220:223], v[70:73]
	v_mfma_f32_16x16x32_bf16 v[70:73], v[172:175], v[224:227], v[70:73]
	s_setprio 0
	s_setprio 1
	v_mfma_f32_16x16x32_bf16 v[122:125], v[176:179], v[196:199], v[122:125]
	v_mfma_f32_16x16x32_bf16 v[122:125], v[184:187], v[200:203], v[122:125]
	v_mfma_f32_16x16x32_bf16 v[114:117], v[188:191], v[196:199], v[114:117]
	v_mfma_f32_16x16x32_bf16 v[114:117], v[192:195], v[200:203], v[114:117]
	v_mfma_f32_16x16x32_bf16 v[106:109], v[176:179], v[204:207], v[106:109]
	v_mfma_f32_16x16x32_bf16 v[106:109], v[184:187], v[208:211], v[106:109]
	v_mfma_f32_16x16x32_bf16 v[98:101], v[188:191], v[204:207], v[98:101]
	v_mfma_f32_16x16x32_bf16 v[98:101], v[192:195], v[208:211], v[98:101]
	v_mfma_f32_16x16x32_bf16 v[90:93], v[176:179], v[212:215], v[90:93]
	v_mfma_f32_16x16x32_bf16 v[90:93], v[184:187], v[216:219], v[90:93]
	v_mfma_f32_16x16x32_bf16 v[82:85], v[188:191], v[212:215], v[82:85]
	v_mfma_f32_16x16x32_bf16 v[82:85], v[192:195], v[216:219], v[82:85]
	v_mfma_f32_16x16x32_bf16 v[74:77], v[176:179], v[220:223], v[74:77]
	v_mfma_f32_16x16x32_bf16 v[74:77], v[184:187], v[224:227], v[74:77]
	v_mfma_f32_16x16x32_bf16 v[66:69], v[188:191], v[220:223], v[66:69]
	v_mfma_f32_16x16x32_bf16 v[66:69], v[192:195], v[224:227], v[66:69]
	s_setprio 0
	s_barrier
	s_add_i32 s42, s83, s13
	v_lshl_add_u64 v[152:153], v[152:153], 0, s[22:23]
	s_mov_b32 m0, s42
	ds_read_b128 v[196:199], v161 offset:49152
	ds_read_b128 v[200:203], v161 offset:50176
	ds_read_b128 v[204:207], v161 offset:51200
	ds_read_b128 v[208:211], v161 offset:52224
	ds_read_b128 v[212:215], v161 offset:53248
	ds_read_b128 v[216:219], v161 offset:54272
	ds_read_b128 v[220:223], v161 offset:55296
	ds_read_b128 v[224:227], v161 offset:56320
	global_load_lds_dwordx4 v[152:153], off
	s_add_i32 m0, s42, 0x2000
	s_add_u32 s40, s40, 0x100080
	v_lshl_add_u64 v[152:153], v[180:181], 0, s[22:23]
	s_addc_u32 s41, s41, 0
	s_add_i32 s42, s84, s13
	global_load_lds_dwordx4 v[152:153], off
	v_lshl_add_u64 v[152:153], s[40:41], 0, v[132:133]
	s_mov_b32 m0, s42
	s_nop 0
	global_load_lds_dwordx4 v[152:153], off
	v_lshl_add_u64 v[152:153], s[40:41], 0, v[136:137]
	s_add_i32 m0, s42, 0x2000
	s_nop 0
	global_load_lds_dwordx4 v[152:153], off
	v_lshl_add_u64 v[152:153], v[228:229], 0, s[22:23]
	s_mov_b32 m0, s59
	s_nop 0
	global_load_lds_dwordx4 v[152:153], off
	v_lshl_add_u64 v[152:153], v[230:231], 0, s[22:23]
	s_mov_b32 m0, s62
	s_nop 0
	global_load_lds_dwordx4 v[152:153], off
	s_waitcnt vmcnt(8)
	s_waitcnt lgkmcnt(0)
	s_barrier
	s_setprio 1
	s_waitcnt lgkmcnt(0)
	v_mfma_f32_16x16x32_bf16 v[62:65], v[148:151], v[196:199], v[62:65]
	v_mfma_f32_16x16x32_bf16 v[62:65], v[164:167], v[200:203], v[62:65]
	v_mfma_f32_16x16x32_bf16 v[54:57], v[168:171], v[196:199], v[54:57]
	v_mfma_f32_16x16x32_bf16 v[54:57], v[172:175], v[200:203], v[54:57]
	v_mfma_f32_16x16x32_bf16 v[46:49], v[148:151], v[204:207], v[46:49]
	v_mfma_f32_16x16x32_bf16 v[46:49], v[164:167], v[208:211], v[46:49]
	v_mfma_f32_16x16x32_bf16 v[38:41], v[168:171], v[204:207], v[38:41]
	v_mfma_f32_16x16x32_bf16 v[38:41], v[172:175], v[208:211], v[38:41]
	v_mfma_f32_16x16x32_bf16 v[30:33], v[148:151], v[212:215], v[30:33]
	v_mfma_f32_16x16x32_bf16 v[30:33], v[164:167], v[216:219], v[30:33]
	v_mfma_f32_16x16x32_bf16 v[22:25], v[168:171], v[212:215], v[22:25]
	v_mfma_f32_16x16x32_bf16 v[22:25], v[172:175], v[216:219], v[22:25]
	v_mfma_f32_16x16x32_bf16 v[14:17], v[148:151], v[220:223], v[14:17]
	v_mfma_f32_16x16x32_bf16 v[14:17], v[164:167], v[224:227], v[14:17]
	v_mfma_f32_16x16x32_bf16 v[6:9], v[168:171], v[220:223], v[6:9]
	v_mfma_f32_16x16x32_bf16 v[6:9], v[172:175], v[224:227], v[6:9]
	s_setprio 0
	s_setprio 1
	v_mfma_f32_16x16x32_bf16 v[58:61], v[176:179], v[196:199], v[58:61]
	v_mfma_f32_16x16x32_bf16 v[58:61], v[184:187], v[200:203], v[58:61]
	v_mfma_f32_16x16x32_bf16 v[50:53], v[188:191], v[196:199], v[50:53]
	v_mfma_f32_16x16x32_bf16 v[50:53], v[192:195], v[200:203], v[50:53]
	v_mfma_f32_16x16x32_bf16 v[42:45], v[176:179], v[204:207], v[42:45]
	v_mfma_f32_16x16x32_bf16 v[42:45], v[184:187], v[208:211], v[42:45]
	v_mfma_f32_16x16x32_bf16 v[34:37], v[188:191], v[204:207], v[34:37]
	v_mfma_f32_16x16x32_bf16 v[34:37], v[192:195], v[208:211], v[34:37]
	v_mfma_f32_16x16x32_bf16 v[26:29], v[176:179], v[212:215], v[26:29]
	v_mfma_f32_16x16x32_bf16 v[26:29], v[184:187], v[216:219], v[26:29]
	v_mfma_f32_16x16x32_bf16 v[18:21], v[188:191], v[212:215], v[18:21]
	v_mfma_f32_16x16x32_bf16 v[18:21], v[192:195], v[216:219], v[18:21]
	v_mfma_f32_16x16x32_bf16 v[10:13], v[176:179], v[220:223], v[10:13]
	v_mfma_f32_16x16x32_bf16 v[10:13], v[184:187], v[224:227], v[10:13]
	v_mfma_f32_16x16x32_bf16 v[2:5], v[188:191], v[220:223], v[2:5]
	v_mfma_f32_16x16x32_bf16 v[2:5], v[192:195], v[224:227], v[2:5]
	s_setprio 0
	s_barrier
	s_add_i32 s82, s82, 2
	s_add_u32 s6, s6, 0x100
	s_addc_u32 s7, s7, 0
	s_add_u32 s80, s80, 0x100
	s_addc_u32 s81, s81, 0
	s_cmp_gt_u32 s82, 61
	s_cbranch_scc0 .LBB0_2720
	s_and_b64 vcc, exec, s[24:25]
	s_cbranch_vccz .LBB0_2723
	s_barrier

.LBB0_2805:
	ds_read_b128 v[130:133], v163
	ds_read_b128 v[134:137], v163 offset:1024
	ds_read_b128 v[138:141], v163 offset:2048
	ds_read_b128 v[142:145], v163 offset:3072
	ds_read_b128 v[146:149], v188
	ds_read_b128 v[150:153], v188 offset:1024
	ds_read_b128 v[174:177], v188 offset:2048
	ds_read_b128 v[178:181], v188 offset:3072
	s_add_u32 s28, s26, 0xffd50080
	s_addc_u32 s29, s27, -1
	s_cmpk_eq_i32 s62, 0xa8
	s_cselect_b32 s37, s7, s29
	s_cselect_b32 s36, s6, s28
	s_cselect_b32 s29, s25, s59
	s_cselect_b32 s28, s24, s12
	v_lshl_add_u64 v[220:221], s[26:27], 0, v[166:167]
	s_add_i32 m0, s38, 0xc000
	ds_read_b128 v[184:187], v189
	ds_read_b128 v[192:195], v189 offset:1024
	ds_read_b128 v[196:199], v189 offset:2048
	ds_read_b128 v[200:203], v189 offset:3072
	ds_read_b128 v[204:207], v189 offset:4096
	ds_read_b128 v[208:211], v189 offset:5120
	ds_read_b128 v[212:215], v189 offset:6144
	ds_read_b128 v[216:219], v189 offset:7168
	global_load_lds_dwordx4 v[220:221], off
	v_lshl_add_u64 v[220:221], s[26:27], 0, v[168:169]
	s_add_i32 m0, s38, 0xe000
	s_nop 0
	global_load_lds_dwordx4 v[220:221], off
	s_waitcnt vmcnt(8)
	s_waitcnt lgkmcnt(0)
	s_barrier
	s_setprio 1
	s_waitcnt lgkmcnt(0)
	v_mfma_f32_16x16x32_bf16 v[126:129], v[130:133], v[184:187], v[126:129]
	v_mfma_f32_16x16x32_bf16 v[126:129], v[134:137], v[192:195], v[126:129]
	v_mfma_f32_16x16x32_bf16 v[122:125], v[138:141], v[184:187], v[122:125]
	v_mfma_f32_16x16x32_bf16 v[122:125], v[142:145], v[192:195], v[122:125]
	v_mfma_f32_16x16x32_bf16 v[110:113], v[130:133], v[196:199], v[110:113]
	v_mfma_f32_16x16x32_bf16 v[110:113], v[134:137], v[200:203], v[110:113]
	v_mfma_f32_16x16x32_bf16 v[106:109], v[138:141], v[196:199], v[106:109]
	v_mfma_f32_16x16x32_bf16 v[106:109], v[142:145], v[200:203], v[106:109]
	v_mfma_f32_16x16x32_bf16 v[94:97], v[130:133], v[204:207], v[94:97]
	v_mfma_f32_16x16x32_bf16 v[94:97], v[134:137], v[208:211], v[94:97]
	v_mfma_f32_16x16x32_bf16 v[90:93], v[138:141], v[204:207], v[90:93]
	v_mfma_f32_16x16x32_bf16 v[90:93], v[142:145], v[208:211], v[90:93]
	v_mfma_f32_16x16x32_bf16 v[78:81], v[130:133], v[212:215], v[78:81]
	v_mfma_f32_16x16x32_bf16 v[78:81], v[134:137], v[216:219], v[78:81]
	v_mfma_f32_16x16x32_bf16 v[74:77], v[138:141], v[212:215], v[74:77]
	v_mfma_f32_16x16x32_bf16 v[74:77], v[142:145], v[216:219], v[74:77]
	s_setprio 0
	s_setprio 1
	v_mfma_f32_16x16x32_bf16 v[118:121], v[146:149], v[184:187], v[118:121]
	v_mfma_f32_16x16x32_bf16 v[118:121], v[150:153], v[192:195], v[118:121]
	v_mfma_f32_16x16x32_bf16 v[114:117], v[174:177], v[184:187], v[114:117]
	v_mfma_f32_16x16x32_bf16 v[114:117], v[178:181], v[192:195], v[114:117]
	v_mfma_f32_16x16x32_bf16 v[102:105], v[146:149], v[196:199], v[102:105]
	v_mfma_f32_16x16x32_bf16 v[102:105], v[150:153], v[200:203], v[102:105]
	v_mfma_f32_16x16x32_bf16 v[98:101], v[174:177], v[196:199], v[98:101]
	v_mfma_f32_16x16x32_bf16 v[98:101], v[178:181], v[200:203], v[98:101]
	v_mfma_f32_16x16x32_bf16 v[86:89], v[146:149], v[204:207], v[86:89]
	v_mfma_f32_16x16x32_bf16 v[86:89], v[150:153], v[208:211], v[86:89]
	v_mfma_f32_16x16x32_bf16 v[82:85], v[174:177], v[204:207], v[82:85]
	v_mfma_f32_16x16x32_bf16 v[82:85], v[178:181], v[208:211], v[82:85]
	v_mfma_f32_16x16x32_bf16 v[70:73], v[146:149], v[212:215], v[70:73]
	v_mfma_f32_16x16x32_bf16 v[70:73], v[150:153], v[216:219], v[70:73]
	v_mfma_f32_16x16x32_bf16 v[66:69], v[174:177], v[212:215], v[66:69]
	v_mfma_f32_16x16x32_bf16 v[66:69], v[178:181], v[216:219], v[66:69]
	s_setprio 0
	s_barrier
	s_add_i32 s63, s47, s35
	v_lshl_add_u64 v[220:221], s[28:29], 0, v[156:157]
	s_mov_b32 m0, s63
	ds_read_b128 v[184:187], v189 offset:16384
	ds_read_b128 v[192:195], v189 offset:17408
	ds_read_b128 v[196:199], v189 offset:18432
	ds_read_b128 v[200:203], v189 offset:19456
	ds_read_b128 v[204:207], v189 offset:20480
	ds_read_b128 v[208:211], v189 offset:21504
	ds_read_b128 v[212:215], v189 offset:22528
	ds_read_b128 v[216:219], v189 offset:23552
	global_load_lds_dwordx4 v[220:221], off
	s_add_i32 m0, s63, 0x2000
	s_add_u32 s66, s28, 0x2b0000
	v_lshl_add_u64 v[222:223], s[28:29], 0, v[160:161]
	s_addc_u32 s67, s29, 0
	s_add_i32 s63, s48, s35
	global_load_lds_dwordx4 v[222:223], off
	v_lshl_add_u64 v[224:225], s[66:67], 0, v[156:157]
	s_mov_b32 m0, s63
	v_lshl_add_u64 v[226:227], s[36:37], 0, v[158:159]
	global_load_lds_dwordx4 v[224:225], off
	v_lshl_add_u64 v[224:225], s[66:67], 0, v[160:161]
	s_add_i32 m0, s63, 0x2000
	s_nop 0
	global_load_lds_dwordx4 v[224:225], off
	v_lshl_add_u64 v[224:225], s[36:37], 0, v[154:155]
	s_mov_b32 m0, s38
	s_nop 0
	global_load_lds_dwordx4 v[224:225], off
	s_mov_b32 m0, s39
	s_nop 0
	global_load_lds_dwordx4 v[226:227], off
	s_waitcnt vmcnt(8)
	s_waitcnt lgkmcnt(0)
	s_barrier
	s_setprio 1
	s_waitcnt lgkmcnt(0)
	v_mfma_f32_16x16x32_bf16 v[62:65], v[130:133], v[184:187], v[62:65]
	v_mfma_f32_16x16x32_bf16 v[62:65], v[134:137], v[192:195], v[62:65]
	v_mfma_f32_16x16x32_bf16 v[58:61], v[138:141], v[184:187], v[58:61]
	v_mfma_f32_16x16x32_bf16 v[58:61], v[142:145], v[192:195], v[58:61]
	v_mfma_f32_16x16x32_bf16 v[46:49], v[130:133], v[196:199], v[46:49]
	v_mfma_f32_16x16x32_bf16 v[46:49], v[134:137], v[200:203], v[46:49]
	v_mfma_f32_16x16x32_bf16 v[42:45], v[138:141], v[196:199], v[42:45]
	v_mfma_f32_16x16x32_bf16 v[42:45], v[142:145], v[200:203], v[42:45]
	v_mfma_f32_16x16x32_bf16 v[30:33], v[130:133], v[204:207], v[30:33]
	v_mfma_f32_16x16x32_bf16 v[30:33], v[134:137], v[208:211], v[30:33]
	v_mfma_f32_16x16x32_bf16 v[26:29], v[138:141], v[204:207], v[26:29]
	v_mfma_f32_16x16x32_bf16 v[26:29], v[142:145], v[208:211], v[26:29]
	v_mfma_f32_16x16x32_bf16 v[14:17], v[130:133], v[212:215], v[14:17]
	v_mfma_f32_16x16x32_bf16 v[14:17], v[134:137], v[216:219], v[14:17]
	v_mfma_f32_16x16x32_bf16 v[10:13], v[138:141], v[212:215], v[10:13]
	v_mfma_f32_16x16x32_bf16 v[10:13], v[142:145], v[216:219], v[10:13]
	s_setprio 0
	s_setprio 1
	v_mfma_f32_16x16x32_bf16 v[54:57], v[146:149], v[184:187], v[54:57]
	v_mfma_f32_16x16x32_bf16 v[54:57], v[150:153], v[192:195], v[54:57]
	v_mfma_f32_16x16x32_bf16 v[50:53], v[174:177], v[184:187], v[50:53]
	v_mfma_f32_16x16x32_bf16 v[50:53], v[178:181], v[192:195], v[50:53]
	v_mfma_f32_16x16x32_bf16 v[38:41], v[146:149], v[196:199], v[38:41]
	v_mfma_f32_16x16x32_bf16 v[38:41], v[150:153], v[200:203], v[38:41]
	v_mfma_f32_16x16x32_bf16 v[34:37], v[174:177], v[196:199], v[34:37]
	v_mfma_f32_16x16x32_bf16 v[34:37], v[178:181], v[200:203], v[34:37]
	v_mfma_f32_16x16x32_bf16 v[22:25], v[146:149], v[204:207], v[22:25]
	v_mfma_f32_16x16x32_bf16 v[22:25], v[150:153], v[208:211], v[22:25]
	v_mfma_f32_16x16x32_bf16 v[18:21], v[174:177], v[204:207], v[18:21]
	v_mfma_f32_16x16x32_bf16 v[18:21], v[178:181], v[208:211], v[18:21]
	v_mfma_f32_16x16x32_bf16 v[6:9], v[146:149], v[212:215], v[6:9]
	v_mfma_f32_16x16x32_bf16 v[6:9], v[150:153], v[216:219], v[6:9]
	v_mfma_f32_16x16x32_bf16 v[2:5], v[174:177], v[212:215], v[2:5]
	v_mfma_f32_16x16x32_bf16 v[2:5], v[178:181], v[216:219], v[2:5]
	s_setprio 0
	s_barrier
	s_add_i32 s63, 0, 0x18000
	s_add_i32 s65, 0, 0x1c000
	v_add_u32_e32 v142, s63, v1
	v_add_u32_e32 v178, s65, v1
	ds_read_b128 v[130:133], v142
	ds_read_b128 v[134:137], v142 offset:1024
	ds_read_b128 v[138:141], v142 offset:2048
	ds_read_b128 v[142:145], v142 offset:3072
	ds_read_b128 v[146:149], v178
	ds_read_b128 v[150:153], v178 offset:1024
	ds_read_b128 v[174:177], v178 offset:2048
	ds_read_b128 v[178:181], v178 offset:3072
	s_add_u32 s36, s36, 0x2b0000
	s_addc_u32 s37, s37, 0
	s_mov_b32 m0, s40
	v_lshl_add_u64 v[228:229], s[36:37], 0, v[154:155]
	ds_read_b128 v[184:187], v189 offset:32768
	ds_read_b128 v[192:195], v189 offset:33792
	ds_read_b128 v[196:199], v189 offset:34816
	ds_read_b128 v[200:203], v189 offset:35840
	ds_read_b128 v[204:207], v189 offset:36864
	ds_read_b128 v[208:211], v189 offset:37888
	ds_read_b128 v[212:215], v189 offset:38912
	ds_read_b128 v[216:219], v189 offset:39936
	global_load_lds_dwordx4 v[228:229], off
	v_lshl_add_u64 v[228:229], s[36:37], 0, v[158:159]
	s_mov_b32 m0, s41
	s_nop 0
	global_load_lds_dwordx4 v[228:229], off
	s_waitcnt vmcnt(8)
	s_waitcnt lgkmcnt(0)
	s_barrier
	s_setprio 1
	s_waitcnt lgkmcnt(0)
	v_mfma_f32_16x16x32_bf16 v[126:129], v[130:133], v[184:187], v[126:129]
	v_mfma_f32_16x16x32_bf16 v[126:129], v[134:137], v[192:195], v[126:129]
	v_mfma_f32_16x16x32_bf16 v[122:125], v[138:141], v[184:187], v[122:125]
	v_mfma_f32_16x16x32_bf16 v[122:125], v[142:145], v[192:195], v[122:125]
	v_mfma_f32_16x16x32_bf16 v[110:113], v[130:133], v[196:199], v[110:113]
	v_mfma_f32_16x16x32_bf16 v[110:113], v[134:137], v[200:203], v[110:113]
	v_mfma_f32_16x16x32_bf16 v[106:109], v[138:141], v[196:199], v[106:109]
	v_mfma_f32_16x16x32_bf16 v[106:109], v[142:145], v[200:203], v[106:109]
	v_mfma_f32_16x16x32_bf16 v[94:97], v[130:133], v[204:207], v[94:97]
	v_mfma_f32_16x16x32_bf16 v[94:97], v[134:137], v[208:211], v[94:97]
	v_mfma_f32_16x16x32_bf16 v[90:93], v[138:141], v[204:207], v[90:93]
	v_mfma_f32_16x16x32_bf16 v[90:93], v[142:145], v[208:211], v[90:93]
	v_mfma_f32_16x16x32_bf16 v[78:81], v[130:133], v[212:215], v[78:81]
	v_mfma_f32_16x16x32_bf16 v[78:81], v[134:137], v[216:219], v[78:81]
	v_mfma_f32_16x16x32_bf16 v[74:77], v[138:141], v[212:215], v[74:77]
	v_mfma_f32_16x16x32_bf16 v[74:77], v[142:145], v[216:219], v[74:77]
	s_setprio 0
	s_setprio 1
	v_mfma_f32_16x16x32_bf16 v[118:121], v[146:149], v[184:187], v[118:121]
	v_mfma_f32_16x16x32_bf16 v[118:121], v[150:153], v[192:195], v[118:121]
	v_mfma_f32_16x16x32_bf16 v[114:117], v[174:177], v[184:187], v[114:117]
	v_mfma_f32_16x16x32_bf16 v[114:117], v[178:181], v[192:195], v[114:117]
	v_mfma_f32_16x16x32_bf16 v[102:105], v[146:149], v[196:199], v[102:105]
	v_mfma_f32_16x16x32_bf16 v[102:105], v[150:153], v[200:203], v[102:105]
	v_mfma_f32_16x16x32_bf16 v[98:101], v[174:177], v[196:199], v[98:101]
	v_mfma_f32_16x16x32_bf16 v[98:101], v[178:181], v[200:203], v[98:101]
	v_mfma_f32_16x16x32_bf16 v[86:89], v[146:149], v[204:207], v[86:89]
	v_mfma_f32_16x16x32_bf16 v[86:89], v[150:153], v[208:211], v[86:89]
	v_mfma_f32_16x16x32_bf16 v[82:85], v[174:177], v[204:207], v[82:85]
	v_mfma_f32_16x16x32_bf16 v[82:85], v[178:181], v[208:211], v[82:85]
	v_mfma_f32_16x16x32_bf16 v[70:73], v[146:149], v[212:215], v[70:73]
	v_mfma_f32_16x16x32_bf16 v[70:73], v[150:153], v[216:219], v[70:73]
	v_mfma_f32_16x16x32_bf16 v[66:69], v[174:177], v[212:215], v[66:69]
	v_mfma_f32_16x16x32_bf16 v[66:69], v[178:181], v[216:219], v[66:69]
	s_setprio 0
	s_barrier
	s_add_i32 s36, s63, s35
	v_lshl_add_u64 v[220:221], v[220:221], 0, s[20:21]
	s_mov_b32 m0, s36
	ds_read_b128 v[184:187], v189 offset:49152
	ds_read_b128 v[192:195], v189 offset:50176
	ds_read_b128 v[196:199], v189 offset:51200
	ds_read_b128 v[200:203], v189 offset:52224
	ds_read_b128 v[204:207], v189 offset:53248
	ds_read_b128 v[208:211], v189 offset:54272
	ds_read_b128 v[212:215], v189 offset:55296
	ds_read_b128 v[216:219], v189 offset:56320
	global_load_lds_dwordx4 v[220:221], off
	s_add_i32 m0, s36, 0x2000
	s_add_u32 s28, s28, 0x2b0080
	v_lshl_add_u64 v[220:221], v[222:223], 0, s[20:21]
	s_addc_u32 s29, s29, 0
	s_add_i32 s36, s65, s35
	global_load_lds_dwordx4 v[220:221], off
	v_lshl_add_u64 v[220:221], s[28:29], 0, v[156:157]
	s_mov_b32 m0, s36
	s_nop 0
	global_load_lds_dwordx4 v[220:221], off
	v_lshl_add_u64 v[220:221], s[28:29], 0, v[160:161]
	s_add_i32 m0, s36, 0x2000
	s_nop 0
	global_load_lds_dwordx4 v[220:221], off
	v_lshl_add_u64 v[220:221], v[224:225], 0, s[20:21]
	s_mov_b32 m0, s43
	s_nop 0
	global_load_lds_dwordx4 v[220:221], off
	v_lshl_add_u64 v[220:221], v[226:227], 0, s[20:21]
	s_mov_b32 m0, s44
	s_nop 0
	global_load_lds_dwordx4 v[220:221], off
	s_waitcnt vmcnt(8)
	s_waitcnt lgkmcnt(0)
	s_barrier
	s_setprio 1
	s_waitcnt lgkmcnt(0)
	v_mfma_f32_16x16x32_bf16 v[62:65], v[130:133], v[184:187], v[62:65]
	v_mfma_f32_16x16x32_bf16 v[62:65], v[134:137], v[192:195], v[62:65]
	v_mfma_f32_16x16x32_bf16 v[58:61], v[138:141], v[184:187], v[58:61]
	v_mfma_f32_16x16x32_bf16 v[58:61], v[142:145], v[192:195], v[58:61]
	v_mfma_f32_16x16x32_bf16 v[46:49], v[130:133], v[196:199], v[46:49]
	v_mfma_f32_16x16x32_bf16 v[46:49], v[134:137], v[200:203], v[46:49]
	v_mfma_f32_16x16x32_bf16 v[42:45], v[138:141], v[196:199], v[42:45]
	v_mfma_f32_16x16x32_bf16 v[42:45], v[142:145], v[200:203], v[42:45]
	v_mfma_f32_16x16x32_bf16 v[30:33], v[130:133], v[204:207], v[30:33]
	v_mfma_f32_16x16x32_bf16 v[30:33], v[134:137], v[208:211], v[30:33]
	v_mfma_f32_16x16x32_bf16 v[26:29], v[138:141], v[204:207], v[26:29]
	v_mfma_f32_16x16x32_bf16 v[26:29], v[142:145], v[208:211], v[26:29]
	v_mfma_f32_16x16x32_bf16 v[14:17], v[130:133], v[212:215], v[14:17]
	v_mfma_f32_16x16x32_bf16 v[14:17], v[134:137], v[216:219], v[14:17]
	v_mfma_f32_16x16x32_bf16 v[10:13], v[138:141], v[212:215], v[10:13]
	v_mfma_f32_16x16x32_bf16 v[10:13], v[142:145], v[216:219], v[10:13]
	s_setprio 0
	s_setprio 1
	v_mfma_f32_16x16x32_bf16 v[54:57], v[146:149], v[184:187], v[54:57]
	v_mfma_f32_16x16x32_bf16 v[54:57], v[150:153], v[192:195], v[54:57]
	v_mfma_f32_16x16x32_bf16 v[50:53], v[174:177], v[184:187], v[50:53]
	v_mfma_f32_16x16x32_bf16 v[50:53], v[178:181], v[192:195], v[50:53]
	v_mfma_f32_16x16x32_bf16 v[38:41], v[146:149], v[196:199], v[38:41]
	v_mfma_f32_16x16x32_bf16 v[38:41], v[150:153], v[200:203], v[38:41]
	v_mfma_f32_16x16x32_bf16 v[34:37], v[174:177], v[196:199], v[34:37]
	v_mfma_f32_16x16x32_bf16 v[34:37], v[178:181], v[200:203], v[34:37]
	v_mfma_f32_16x16x32_bf16 v[22:25], v[146:149], v[204:207], v[22:25]
	v_mfma_f32_16x16x32_bf16 v[22:25], v[150:153], v[208:211], v[22:25]
	v_mfma_f32_16x16x32_bf16 v[18:21], v[174:177], v[204:207], v[18:21]
	v_mfma_f32_16x16x32_bf16 v[18:21], v[178:181], v[208:211], v[18:21]
	v_mfma_f32_16x16x32_bf16 v[6:9], v[146:149], v[212:215], v[6:9]
	v_mfma_f32_16x16x32_bf16 v[6:9], v[150:153], v[216:219], v[6:9]
	v_mfma_f32_16x16x32_bf16 v[2:5], v[174:177], v[212:215], v[2:5]
	v_mfma_f32_16x16x32_bf16 v[2:5], v[178:181], v[216:219], v[2:5]
	s_setprio 0
	s_barrier
	s_add_i32 s62, s62, 2
	s_add_u32 s26, s26, 0x100
	s_addc_u32 s27, s27, 0
	s_add_u32 s12, s12, 0x100
	s_addc_u32 s59, s59, 0
	s_cmpk_gt_u32 s62, 0xa9
	s_cbranch_scc0 .LBB0_2805
	s_and_b64 vcc, exec, s[22:23]
	s_cbranch_vccz .LBB0_2808
	s_barrier
